# speedup vs baseline: 1.0114x; 1.0110x over previous
; #define G_STAGE(bufoff, gbase, voff) do { _Pragma("unroll") for (int _i = 0; _i < 2; ++_i) \
;         __builtin_amdgcn_global_load_lds((const unsigned*)((const char*)(gbase) + (voff)[_i]), (LAS unsigned*)(lds + (bufoff) + ldsw + _i * 8192), 16, 0, 0); } while (0)
; #define G_LDA(dst, b, h) do { _Pragma("unroll") for (int m = 0; m < 4; ++m) _Pragma("unroll") for (int k = 0; k < 2; ++k) dst[m][k] = *(const LAS bf16x8*)(lds + G_SA(b, h) + aoff + m * 2048 + k * 1024); } while (0)
; #define G_LDB(dst, b, h) do { _Pragma("unroll") for (int n = 0; n < 2; ++n) _Pragma("unroll") for (int k = 0; k < 2; ++k) dst[n][k] = *(const LAS bf16x8*)(lds + G_SB(b, h) + boff + n * 2048 + k * 1024); } while (0)
; #define G_MMA(ai, bj, At, Bt) do { __builtin_amdgcn_s_setprio(1); _Pragma("unroll") for (int m = 0; m < 4; ++m) _Pragma("unroll") for (int n = 0; n < 2; ++n) _Pragma("unroll") for (int k = 0; k < 2; ++k) \
;         acc[ai][bj][m][n] = __builtin_amdgcn_mfma_f32_16x16x32_bf16(Bt[n][k], At[m][k], acc[ai][bj][m][n], 0, 0, 0); __builtin_amdgcn_s_setprio(0); } while (0)
; #define G_WAIT_L(n) asm volatile("s_waitcnt lgkmcnt(" #n ")" ::: "memory")
; #define G_BAR __builtin_amdgcn_s_barrier()
; #define G_SCHED __builtin_amdgcn_sched_barrier(0)
; template <class J>
; DI void gemm_phase(LAS unsigned char* lds, const J& job) {
;     ...
;     for (int t = 0; t < nt; t += 2) {
;       const bool last = (t == nt - 2);
;       const char* a1 = cA + G_KT(t + 1);
;       const char* a2 = last ? nA + G_KT(0) : cA + G_KT(t + 2); const char* b2 = last ? nB + G_KT(0) : cB + G_KT(t + 2);
;       const char* a3 = last ? nA + G_KT(1) : cA + G_KT(t + 3); const char* b3 = last ? nB + G_KT(1) : cB + G_KT(t + 3);
;       G_LDB(B0, 0, 0); G_SCHED; G_LDA(At, 0, 0); G_STAGE(G_SA(1, 1), a1 + hstepA, voffA);
;       G_WAIT_L(8); G_BAR; G_WAIT_L(0); G_MMA(0, 0, At, B0); G_BAR; G_SCHED;
;       G_LDB(B1, 0, 1); G_STAGE(G_SB(0, 0), b2, voffB);
;       G_BAR; G_WAIT_L(0); G_MMA(0, 1, At, B1); G_BAR;
;       G_LDA(At, 0, 1); G_STAGE(G_SA(0, 0), a2, voffA);
;       G_BAR; G_WAIT_L(0); G_MMA(1, 0, At, B0); G_BAR; G_SCHED;
.LBB0_42:
	s_add_i32 s1, s57, 0xffffff80
	s_and_b32 s0, s44, 0xf80
	s_and_b32 s1, s1, 0xf00
	s_add_u32 s2, s70, s1
	s_addc_u32 s72, s71, 0
	s_add_u32 s1, s68, s1
	s_addc_u32 s73, s69, 0
	s_and_b32 s74, s57, 0xf80
	s_add_u32 s80, s70, s74
	s_addc_u32 s75, s71, 0
	s_add_u32 s54, s68, s74
	s_addc_u32 s55, s69, 0
	s_cmp_eq_u32 s7, 28
	s_cselect_b32 s77, vcc_lo, s72
	s_cselect_b32 s76, s47, s2
	s_cselect_b32 s79, s33, s73
	s_cselect_b32 s78, vcc_hi, s1
	s_cselect_b32 s75, s4, s75
	s_cselect_b32 s74, s97, s80
	s_cselect_b32 s73, s6, s55
	s_cselect_b32 s72, s5, s54
	s_add_i32 s2, s84, 0x100
	v_add_u32_e32 v140, s2, v162
	ds_read_b128 v[128:131], v140
	ds_read_b128 v[132:135], v140 offset:1024
	ds_read_b128 v[136:139], v140 offset:2048
	ds_read_b128 v[140:143], v140 offset:3072
	s_add_u32 s0, s21, s0
	s_addc_u32 s1, s23, 0
	s_add_i32 m0, s25, 0xc000
	ds_read_b128 v[154:157], v163
	ds_read_b128 v[164:167], v163 offset:1024
	ds_read_b128 v[168:171], v163 offset:2048
	ds_read_b128 v[172:175], v163 offset:3072
	ds_read_b128 v[176:179], v163 offset:4096
	ds_read_b128 v[180:183], v163 offset:5120
	ds_read_b128 v[184:187], v163 offset:6144
	ds_read_b128 v[188:191], v163 offset:7168
	global_load_lds_dwordx4 v148, s[0:1]
	s_add_i32 m0, s25, 0xe000
	s_nop 0
	global_load_lds_dwordx4 v150, s[0:1]
	s_waitcnt lgkmcnt(8)
	s_barrier
	s_waitcnt lgkmcnt(0)
	v_mfma_f32_16x16x32_bf16 v[124:127], v[128:131], v[154:157], v[124:127]
	v_mfma_f32_16x16x32_bf16 v[120:123], v[136:139], v[154:157], v[120:123]
	v_mfma_f32_16x16x32_bf16 v[108:111], v[128:131], v[168:171], v[108:111]
	v_mfma_f32_16x16x32_bf16 v[104:107], v[136:139], v[168:171], v[104:107]
	v_mfma_f32_16x16x32_bf16 v[92:95], v[128:131], v[176:179], v[92:95]
	v_mfma_f32_16x16x32_bf16 v[88:91], v[136:139], v[176:179], v[88:91]
	v_mfma_f32_16x16x32_bf16 v[76:79], v[128:131], v[184:187], v[76:79]
	v_mfma_f32_16x16x32_bf16 v[72:75], v[136:139], v[184:187], v[72:75]
	v_mfma_f32_16x16x32_bf16 v[124:127], v[132:135], v[164:167], v[124:127]
	v_mfma_f32_16x16x32_bf16 v[120:123], v[140:143], v[164:167], v[120:123]
	v_mfma_f32_16x16x32_bf16 v[108:111], v[132:135], v[172:175], v[108:111]
	v_mfma_f32_16x16x32_bf16 v[104:107], v[140:143], v[172:175], v[104:107]
	v_mfma_f32_16x16x32_bf16 v[92:95], v[132:135], v[180:183], v[92:95]
	v_mfma_f32_16x16x32_bf16 v[88:91], v[140:143], v[180:183], v[88:91]
	v_mfma_f32_16x16x32_bf16 v[76:79], v[132:135], v[188:191], v[76:79]
	v_mfma_f32_16x16x32_bf16 v[72:75], v[140:143], v[188:191], v[72:75]
	s_barrier
	s_add_i32 s54, s85, 0x100
	v_add_u32_e32 v158, s54, v162
	s_add_i32 s0, s2, s14
	ds_read_b128 v[192:195], v158
	ds_read_b128 v[196:199], v158 offset:1024
	ds_read_b128 v[200:203], v158 offset:2048
	ds_read_b128 v[204:207], v158 offset:3072
	s_mov_b32 m0, s0
	s_nop 0
	global_load_lds_dwordx4 v146, s[78:79]
	s_add_i32 m0, s0, 0x2000
	s_nop 0
	global_load_lds_dwordx4 v152, s[78:79]
	s_barrier
	s_waitcnt lgkmcnt(0)
	v_mfma_f32_16x16x32_bf16 v[116:119], v[192:195], v[154:157], v[116:119]
	v_mfma_f32_16x16x32_bf16 v[112:115], v[200:203], v[154:157], v[112:115]
	v_mfma_f32_16x16x32_bf16 v[100:103], v[192:195], v[168:171], v[100:103]
	v_mfma_f32_16x16x32_bf16 v[96:99], v[200:203], v[168:171], v[96:99]
	v_mfma_f32_16x16x32_bf16 v[84:87], v[192:195], v[176:179], v[84:87]
	v_mfma_f32_16x16x32_bf16 v[80:83], v[200:203], v[176:179], v[80:83]
	v_mfma_f32_16x16x32_bf16 v[68:71], v[192:195], v[184:187], v[68:71]
	v_mfma_f32_16x16x32_bf16 v[64:67], v[200:203], v[184:187], v[64:67]
	v_mfma_f32_16x16x32_bf16 v[116:119], v[196:199], v[164:167], v[116:119]
	v_mfma_f32_16x16x32_bf16 v[112:115], v[204:207], v[164:167], v[112:115]
	v_mfma_f32_16x16x32_bf16 v[100:103], v[196:199], v[172:175], v[100:103]
	v_mfma_f32_16x16x32_bf16 v[96:99], v[204:207], v[172:175], v[96:99]
	v_mfma_f32_16x16x32_bf16 v[84:87], v[196:199], v[180:183], v[84:87]
	v_mfma_f32_16x16x32_bf16 v[80:83], v[204:207], v[180:183], v[80:83]
	v_mfma_f32_16x16x32_bf16 v[68:71], v[196:199], v[188:191], v[68:71]
	v_mfma_f32_16x16x32_bf16 v[64:67], v[204:207], v[188:191], v[64:67]
	s_mov_b32 m0, s25
	s_barrier
	ds_read_b128 v[154:157], v163 offset:16384
	ds_read_b128 v[164:167], v163 offset:17408
	ds_read_b128 v[168:171], v163 offset:18432
	ds_read_b128 v[172:175], v163 offset:19456
	ds_read_b128 v[176:179], v163 offset:20480
	ds_read_b128 v[180:183], v163 offset:21504
	ds_read_b128 v[184:187], v163 offset:22528
	ds_read_b128 v[188:191], v163 offset:23552
	global_load_lds_dwordx4 v148, s[76:77]
	s_mov_b32 m0, s36
	s_nop 0
	global_load_lds_dwordx4 v150, s[76:77]
	s_barrier
	s_waitcnt lgkmcnt(0)
	v_mfma_f32_16x16x32_bf16 v[60:63], v[128:131], v[154:157], v[60:63]
	v_mfma_f32_16x16x32_bf16 v[56:59], v[136:139], v[154:157], v[56:59]
	v_mfma_f32_16x16x32_bf16 v[44:47], v[128:131], v[168:171], v[44:47]
	v_mfma_f32_16x16x32_bf16 v[40:43], v[136:139], v[168:171], v[40:43]
	v_mfma_f32_16x16x32_bf16 v[28:31], v[128:131], v[176:179], v[28:31]
	v_mfma_f32_16x16x32_bf16 v[24:27], v[136:139], v[176:179], v[24:27]
	v_mfma_f32_16x16x32_bf16 v[20:23], v[128:131], v[184:187], v[20:23]
	v_mfma_f32_16x16x32_bf16 v[12:15], v[136:139], v[184:187], v[12:15]
	v_mfma_f32_16x16x32_bf16 v[60:63], v[132:135], v[164:167], v[60:63]
	v_mfma_f32_16x16x32_bf16 v[56:59], v[140:143], v[164:167], v[56:59]
	v_mfma_f32_16x16x32_bf16 v[44:47], v[132:135], v[172:175], v[44:47]
	v_mfma_f32_16x16x32_bf16 v[40:43], v[140:143], v[172:175], v[40:43]
	v_mfma_f32_16x16x32_bf16 v[28:31], v[132:135], v[180:183], v[28:31]
	v_mfma_f32_16x16x32_bf16 v[24:27], v[140:143], v[180:183], v[24:27]
	v_mfma_f32_16x16x32_bf16 v[20:23], v[132:135], v[188:191], v[20:23]
	v_mfma_f32_16x16x32_bf16 v[12:15], v[140:143], v[188:191], v[12:15]
	s_barrier
; #define G_STAGE(bufoff, gbase, voff) do { _Pragma("unroll") for (int _i = 0; _i < 2; ++_i) \
;         __builtin_amdgcn_global_load_lds((const unsigned*)((const char*)(gbase) + (voff)[_i]), (LAS unsigned*)(lds + (bufoff) + ldsw + _i * 8192), 16, 0, 0); } while (0)
; #define G_LDA(dst, b, h) do { _Pragma("unroll") for (int m = 0; m < 4; ++m) _Pragma("unroll") for (int k = 0; k < 2; ++k) dst[m][k] = *(const LAS bf16x8*)(lds + G_SA(b, h) + aoff + m * 2048 + k * 1024); } while (0)
; #define G_LDB(dst, b, h) do { _Pragma("unroll") for (int n = 0; n < 2; ++n) _Pragma("unroll") for (int k = 0; k < 2; ++k) dst[n][k] = *(const LAS bf16x8*)(lds + G_SB(b, h) + boff + n * 2048 + k * 1024); } while (0)
; #define G_MMA(ai, bj, At, Bt) do { __builtin_amdgcn_s_setprio(1); _Pragma("unroll") for (int m = 0; m < 4; ++m) _Pragma("unroll") for (int n = 0; n < 2; ++n) _Pragma("unroll") for (int k = 0; k < 2; ++k) \
;         acc[ai][bj][m][n] = __builtin_amdgcn_mfma_f32_16x16x32_bf16(Bt[n][k], At[m][k], acc[ai][bj][m][n], 0, 0, 0); __builtin_amdgcn_s_setprio(0); } while (0)
; #define G_WAIT_V(n) asm volatile("s_waitcnt vmcnt(" #n ")" ::: "memory")
; #define G_WAIT_L(n) asm volatile("s_waitcnt lgkmcnt(" #n ")" ::: "memory")
; #define G_BAR __builtin_amdgcn_s_barrier()
; #define G_SCHED __builtin_amdgcn_sched_barrier(0)
; template <class J>
; DI void gemm_phase(LAS unsigned char* lds, const J& job) {
;     ...
;       G_STAGE(G_SB(0, 1), b2 + hstepB, voffB);
;       G_WAIT_V(6); G_BAR; G_MMA(1, 1, At, B1); G_BAR;
;       G_LDB(B0, 1, 0); G_SCHED; G_LDA(At, 1, 0); G_STAGE(G_SA(0, 1), a2 + hstepA, voffA);
;       G_WAIT_L(8); G_BAR; G_WAIT_L(0); G_MMA(0, 0, At, B0); G_BAR; G_SCHED;
;       G_LDB(B1, 1, 1); G_STAGE(G_SB(1, 0), b3, voffB);
;       G_BAR; G_WAIT_L(0); G_MMA(0, 1, At, B1); G_BAR;
;       G_LDA(At, 1, 1); G_STAGE(G_SA(1, 0), a3, voffA);
	s_add_u32 s0, s78, 0x80000
	s_addc_u32 s1, s79, 0
	s_add_i32 s2, s54, s14
	s_mov_b32 m0, s2
	s_nop 0
	global_load_lds_dwordx4 v146, s[0:1]
	s_add_i32 m0, s2, 0x2000
	s_nop 0
	global_load_lds_dwordx4 v152, s[0:1]
	s_waitcnt vmcnt(6)
	s_barrier
	v_mfma_f32_16x16x32_bf16 v[52:55], v[192:195], v[154:157], v[52:55]
	v_mfma_f32_16x16x32_bf16 v[48:51], v[200:203], v[154:157], v[48:51]
	v_mfma_f32_16x16x32_bf16 v[36:39], v[192:195], v[168:171], v[36:39]
	v_mfma_f32_16x16x32_bf16 v[32:35], v[200:203], v[168:171], v[32:35]
	v_mfma_f32_16x16x32_bf16 v[16:19], v[192:195], v[176:179], v[16:19]
	v_mfma_f32_16x16x32_bf16 v[8:11], v[200:203], v[176:179], v[8:11]
	v_mfma_f32_16x16x32_bf16 v[4:7], v[192:195], v[184:187], v[4:7]
	v_mfma_f32_16x16x32_bf16 v[0:3], v[200:203], v[184:187], v[0:3]
	v_mfma_f32_16x16x32_bf16 v[52:55], v[196:199], v[164:167], v[52:55]
	v_mfma_f32_16x16x32_bf16 v[48:51], v[204:207], v[164:167], v[48:51]
	v_mfma_f32_16x16x32_bf16 v[36:39], v[196:199], v[172:175], v[36:39]
	v_mfma_f32_16x16x32_bf16 v[32:35], v[204:207], v[172:175], v[32:35]
	v_mfma_f32_16x16x32_bf16 v[16:19], v[196:199], v[180:183], v[16:19]
	v_mfma_f32_16x16x32_bf16 v[8:11], v[204:207], v[180:183], v[8:11]
	v_mfma_f32_16x16x32_bf16 v[4:7], v[196:199], v[188:191], v[4:7]
	v_mfma_f32_16x16x32_bf16 v[0:3], v[204:207], v[188:191], v[0:3]
	s_add_i32 s2, s88, 0x100
	v_add_u32_e32 v140, s2, v162
	s_barrier
	ds_read_b128 v[128:131], v140
	ds_read_b128 v[132:135], v140 offset:1024
	ds_read_b128 v[136:139], v140 offset:2048
	ds_read_b128 v[140:143], v140 offset:3072
	s_add_u32 s0, s76, 0x80000
	s_addc_u32 s1, s77, 0
	s_mov_b32 m0, s37
	ds_read_b128 v[154:157], v163 offset:32768
	ds_read_b128 v[164:167], v163 offset:33792
	ds_read_b128 v[168:171], v163 offset:34816
	ds_read_b128 v[172:175], v163 offset:35840
	ds_read_b128 v[176:179], v163 offset:36864
	ds_read_b128 v[180:183], v163 offset:37888
	ds_read_b128 v[184:187], v163 offset:38912
	ds_read_b128 v[188:191], v163 offset:39936
	global_load_lds_dwordx4 v148, s[0:1]
	s_mov_b32 m0, s38
	s_nop 0
	global_load_lds_dwordx4 v150, s[0:1]
	s_waitcnt lgkmcnt(8)
	s_barrier
	s_waitcnt lgkmcnt(0)
	v_mfma_f32_16x16x32_bf16 v[124:127], v[128:131], v[154:157], v[124:127]
	v_mfma_f32_16x16x32_bf16 v[120:123], v[136:139], v[154:157], v[120:123]
	v_mfma_f32_16x16x32_bf16 v[108:111], v[128:131], v[168:171], v[108:111]
	v_mfma_f32_16x16x32_bf16 v[104:107], v[136:139], v[168:171], v[104:107]
	v_mfma_f32_16x16x32_bf16 v[92:95], v[128:131], v[176:179], v[92:95]
	v_mfma_f32_16x16x32_bf16 v[88:91], v[136:139], v[176:179], v[88:91]
	v_mfma_f32_16x16x32_bf16 v[76:79], v[128:131], v[184:187], v[76:79]
	v_mfma_f32_16x16x32_bf16 v[72:75], v[136:139], v[184:187], v[72:75]
	v_mfma_f32_16x16x32_bf16 v[124:127], v[132:135], v[164:167], v[124:127]
	v_mfma_f32_16x16x32_bf16 v[120:123], v[140:143], v[164:167], v[120:123]
	v_mfma_f32_16x16x32_bf16 v[108:111], v[132:135], v[172:175], v[108:111]
	v_mfma_f32_16x16x32_bf16 v[104:107], v[140:143], v[172:175], v[104:107]
	v_mfma_f32_16x16x32_bf16 v[92:95], v[132:135], v[180:183], v[92:95]
	v_mfma_f32_16x16x32_bf16 v[88:91], v[140:143], v[180:183], v[88:91]
	v_mfma_f32_16x16x32_bf16 v[76:79], v[132:135], v[188:191], v[76:79]
	v_mfma_f32_16x16x32_bf16 v[72:75], v[140:143], v[188:191], v[72:75]
	s_barrier
	s_add_i32 s54, s89, 0x100
	v_add_u32_e32 v158, s54, v162
	s_add_i32 s0, s2, s14
	ds_read_b128 v[192:195], v158
	ds_read_b128 v[196:199], v158 offset:1024
	ds_read_b128 v[200:203], v158 offset:2048
	ds_read_b128 v[204:207], v158 offset:3072
	s_mov_b32 m0, s0
	s_nop 0
	global_load_lds_dwordx4 v146, s[72:73]
	s_add_i32 m0, s0, 0x2000
	s_nop 0
	global_load_lds_dwordx4 v152, s[72:73]
	s_barrier
	s_waitcnt lgkmcnt(0)
	v_mfma_f32_16x16x32_bf16 v[116:119], v[192:195], v[154:157], v[116:119]
	v_mfma_f32_16x16x32_bf16 v[112:115], v[200:203], v[154:157], v[112:115]
	v_mfma_f32_16x16x32_bf16 v[100:103], v[192:195], v[168:171], v[100:103]
	v_mfma_f32_16x16x32_bf16 v[96:99], v[200:203], v[168:171], v[96:99]
	v_mfma_f32_16x16x32_bf16 v[84:87], v[192:195], v[176:179], v[84:87]
	v_mfma_f32_16x16x32_bf16 v[80:83], v[200:203], v[176:179], v[80:83]
	v_mfma_f32_16x16x32_bf16 v[68:71], v[192:195], v[184:187], v[68:71]
	v_mfma_f32_16x16x32_bf16 v[64:67], v[200:203], v[184:187], v[64:67]
	v_mfma_f32_16x16x32_bf16 v[116:119], v[196:199], v[164:167], v[116:119]
	v_mfma_f32_16x16x32_bf16 v[112:115], v[204:207], v[164:167], v[112:115]
	v_mfma_f32_16x16x32_bf16 v[100:103], v[196:199], v[172:175], v[100:103]
	v_mfma_f32_16x16x32_bf16 v[96:99], v[204:207], v[172:175], v[96:99]
	v_mfma_f32_16x16x32_bf16 v[84:87], v[196:199], v[180:183], v[84:87]
	v_mfma_f32_16x16x32_bf16 v[80:83], v[204:207], v[180:183], v[80:83]
	v_mfma_f32_16x16x32_bf16 v[68:71], v[196:199], v[188:191], v[68:71]
	v_mfma_f32_16x16x32_bf16 v[64:67], v[204:207], v[188:191], v[64:67]
	s_mov_b32 m0, s87
	s_barrier
	ds_read_b128 v[154:157], v163 offset:49152
	ds_read_b128 v[164:167], v163 offset:50176
	ds_read_b128 v[168:171], v163 offset:51200
	ds_read_b128 v[172:175], v163 offset:52224
	ds_read_b128 v[176:179], v163 offset:53248
	ds_read_b128 v[180:183], v163 offset:54272
	ds_read_b128 v[184:187], v163 offset:55296
	ds_read_b128 v[188:191], v163 offset:56320
	global_load_lds_dwordx4 v148, s[74:75]
	s_mov_b32 m0, s94
	s_nop 0
	global_load_lds_dwordx4 v150, s[74:75]
	s_barrier
; #define G_STAGE(bufoff, gbase, voff) do { _Pragma("unroll") for (int _i = 0; _i < 2; ++_i) \
;         __builtin_amdgcn_global_load_lds((const unsigned*)((const char*)(gbase) + (voff)[_i]), (LAS unsigned*)(lds + (bufoff) + ldsw + _i * 8192), 16, 0, 0); } while (0)
; #define G_MMA(ai, bj, At, Bt) do { __builtin_amdgcn_s_setprio(1); _Pragma("unroll") for (int m = 0; m < 4; ++m) _Pragma("unroll") for (int n = 0; n < 2; ++n) _Pragma("unroll") for (int k = 0; k < 2; ++k) \
;         acc[ai][bj][m][n] = __builtin_amdgcn_mfma_f32_16x16x32_bf16(Bt[n][k], At[m][k], acc[ai][bj][m][n], 0, 0, 0); __builtin_amdgcn_s_setprio(0); } while (0)
; #define G_WAIT_V(n) asm volatile("s_waitcnt vmcnt(" #n ")" ::: "memory")
; #define G_WAIT_L(n) asm volatile("s_waitcnt lgkmcnt(" #n ")" ::: "memory")
; #define G_BAR __builtin_amdgcn_s_barrier()
; #define G_SCHED __builtin_amdgcn_sched_barrier(0)
; template <class J>
; DI void gemm_phase(LAS unsigned char* lds, const J& job) {
;     ...
;       G_BAR; G_WAIT_L(0); G_MMA(1, 0, At, B0); G_BAR; G_SCHED;
;       G_STAGE(G_SB(1, 1), b3 + hstepB, voffB);
;       G_WAIT_V(6); G_BAR; G_MMA(1, 1, At, B1); G_BAR;
;   DI void epi(const Acc& acc, const Unit& u, int wr, int wc, int fr, int fq) const {
;     ...
;     for (int ai = 0; ai < 2; ++ai) {
;       f32x4 res[4][2][2];
; #pragma unroll
;       for (int m = 0; m < 4; ++m) {
;         const int row = u.pm * 256 + ai * HALF + wr * 64 + m * 16 + fr;
;         const float* src = (l == 0) ? xp + (size_t)row * DM : out + (size_t)row * DM;
; #pragma unroll
;         for (int bj = 0; bj < 2; ++bj) { const int col = u.pn * 256 + bj * HALF + wc * 32 + 8 * fq; res[m][bj][0] = *(const f32x4*)(src + col); res[m][bj][1] = *(const f32x4*)(src + col + 4); }
;       }
	s_waitcnt lgkmcnt(0)
	v_mfma_f32_16x16x32_bf16 v[60:63], v[128:131], v[154:157], v[60:63]
	v_mfma_f32_16x16x32_bf16 v[56:59], v[136:139], v[154:157], v[56:59]
	v_mfma_f32_16x16x32_bf16 v[44:47], v[128:131], v[168:171], v[44:47]
	v_mfma_f32_16x16x32_bf16 v[40:43], v[136:139], v[168:171], v[40:43]
	v_mfma_f32_16x16x32_bf16 v[28:31], v[128:131], v[176:179], v[28:31]
	v_mfma_f32_16x16x32_bf16 v[24:27], v[136:139], v[176:179], v[24:27]
	v_mfma_f32_16x16x32_bf16 v[20:23], v[128:131], v[184:187], v[20:23]
	v_mfma_f32_16x16x32_bf16 v[12:15], v[136:139], v[184:187], v[12:15]
	v_mfma_f32_16x16x32_bf16 v[60:63], v[132:135], v[164:167], v[60:63]
	v_mfma_f32_16x16x32_bf16 v[56:59], v[140:143], v[164:167], v[56:59]
	v_mfma_f32_16x16x32_bf16 v[44:47], v[132:135], v[172:175], v[44:47]
	v_mfma_f32_16x16x32_bf16 v[40:43], v[140:143], v[172:175], v[40:43]
	v_mfma_f32_16x16x32_bf16 v[28:31], v[132:135], v[180:183], v[28:31]
	v_mfma_f32_16x16x32_bf16 v[24:27], v[140:143], v[180:183], v[24:27]
	v_mfma_f32_16x16x32_bf16 v[20:23], v[132:135], v[188:191], v[20:23]
	v_mfma_f32_16x16x32_bf16 v[12:15], v[140:143], v[188:191], v[12:15]
	s_barrier
	s_add_u32 s0, s72, 0x80000
	s_addc_u32 s1, s73, 0
	s_add_i32 s2, s54, s14
	s_mov_b32 m0, s2
	s_nop 0
	global_load_lds_dwordx4 v146, s[0:1]
	s_add_i32 m0, s2, 0x2000
	s_nop 0
	global_load_lds_dwordx4 v152, s[0:1]
	s_waitcnt vmcnt(6)
	s_barrier
	v_mfma_f32_16x16x32_bf16 v[52:55], v[192:195], v[154:157], v[52:55]
	v_mfma_f32_16x16x32_bf16 v[48:51], v[200:203], v[154:157], v[48:51]
	v_mfma_f32_16x16x32_bf16 v[36:39], v[192:195], v[168:171], v[36:39]
	v_mfma_f32_16x16x32_bf16 v[32:35], v[200:203], v[168:171], v[32:35]
	v_mfma_f32_16x16x32_bf16 v[16:19], v[192:195], v[176:179], v[16:19]
	v_mfma_f32_16x16x32_bf16 v[8:11], v[200:203], v[176:179], v[8:11]
	v_mfma_f32_16x16x32_bf16 v[4:7], v[192:195], v[184:187], v[4:7]
	v_mfma_f32_16x16x32_bf16 v[0:3], v[200:203], v[184:187], v[0:3]
	v_mfma_f32_16x16x32_bf16 v[52:55], v[196:199], v[164:167], v[52:55]
	v_mfma_f32_16x16x32_bf16 v[48:51], v[204:207], v[164:167], v[48:51]
	v_mfma_f32_16x16x32_bf16 v[36:39], v[196:199], v[172:175], v[36:39]
	v_mfma_f32_16x16x32_bf16 v[32:35], v[204:207], v[172:175], v[32:35]
	v_mfma_f32_16x16x32_bf16 v[16:19], v[196:199], v[180:183], v[16:19]
	v_mfma_f32_16x16x32_bf16 v[8:11], v[204:207], v[180:183], v[8:11]
	v_mfma_f32_16x16x32_bf16 v[4:7], v[196:199], v[188:191], v[4:7]
	v_mfma_f32_16x16x32_bf16 v[0:3], v[204:207], v[188:191], v[0:3]
	s_add_i32 s7, s7, 2
	s_addk_i32 s57, 0x100
	s_addk_i32 s44, 0x100
	s_cmp_gt_u32 s7, 29
	s_barrier
	s_cbranch_scc0 .LBB0_42
	s_lshl_b32 s0, s66, 8
	v_mov_b32_e32 v128, v161
	v_mov_b32_e32 v129, v160
	s_add_i32 s0, s0, s67
	s_and_b64 vcc, exec, s[18:19]
	v_add_u32_e32 v156, s0, v129
	s_lshl_b32 s0, s46, 8
	s_or_b32 s0, s0, s83
	v_lshl_add_u32 v128, v128, 3, s0
	v_ashrrev_i32_e32 v157, 31, v156
	v_ashrrev_i32_e32 v129, 31, v128
	v_lshlrev_b64 v[212:213], 13, v[156:157]
	v_lshl_add_u64 v[130:131], s[8:9], 0, v[212:213]
	v_lshlrev_b64 v[154:155], 2, v[128:129]
	v_lshl_add_u64 v[128:129], v[130:131], 0, v[154:155]
	global_load_dwordx4 v[164:167], v[128:129], off offset:16
	global_load_dwordx4 v[168:171], v[128:129], off
	global_load_dwordx4 v[172:175], v[128:129], off offset:528
	global_load_dwordx4 v[176:179], v[128:129], off offset:512
	v_add_u32_e32 v128, 16, v156
	v_ashrrev_i32_e32 v129, 31, v128
	v_lshlrev_b64 v[214:215], 13, v[128:129]
	v_lshl_add_u64 v[128:129], s[8:9], 0, v[214:215]
	v_lshl_add_u64 v[128:129], v[128:129], 0, v[154:155]
	global_load_dwordx4 v[180:183], v[128:129], off offset:16
	global_load_dwordx4 v[184:187], v[128:129], off
	global_load_dwordx4 v[188:191], v[128:129], off offset:528
	global_load_dwordx4 v[192:195], v[128:129], off offset:512
	v_add_u32_e32 v128, 32, v156
	v_ashrrev_i32_e32 v129, 31, v128
	v_lshlrev_b64 v[216:217], 13, v[128:129]
	v_lshl_add_u64 v[128:129], s[8:9], 0, v[216:217]
	v_lshl_add_u64 v[128:129], v[128:129], 0, v[154:155]
	global_load_dwordx4 v[196:199], v[128:129], off offset:16
	global_load_dwordx4 v[200:203], v[128:129], off
	global_load_dwordx4 v[204:207], v[128:129], off offset:528
	global_load_dwordx4 v[208:211], v[128:129], off offset:512
	v_add_u32_e32 v128, 48, v156
	v_ashrrev_i32_e32 v129, 31, v128
	v_lshlrev_b64 v[158:159], 13, v[128:129]
	v_lshl_add_u64 v[128:129], s[8:9], 0, v[158:159]
	v_lshl_add_u64 v[136:137], v[128:129], 0, v[154:155]
	global_load_dwordx4 v[132:135], v[136:137], off offset:16
	global_load_dwordx4 v[140:143], v[136:137], off
	global_load_dwordx4 v[128:131], v[136:137], off offset:528
	s_nop 0
	global_load_dwordx4 v[136:139], v[136:137], off offset:512
	v_lshl_add_u64 v[212:213], s[16:17], 0, v[212:213]
	s_mov_b32 s46, s22
	s_mov_b32 s66, s20
	s_mov_b64 s[68:69], s[64:65]
	s_mov_b64 s[70:71], s[62:63]
	s_movk_i32 s54, 0x4000
	s_movk_i32 s55, 0x6000
	v_readlane_b32 s0, v255, 23
	s_cmpk_gt_u32 s0, 0xff
	s_cbranch_scc1 .Lds_out_x
	s_barrier

; #define G_STAGE(bufoff, gbase, voff) do { _Pragma("unroll") for (int _i = 0; _i < 2; ++_i) \
;         __builtin_amdgcn_global_load_lds((const unsigned*)((const char*)(gbase) + (voff)[_i]), (LAS unsigned*)(lds + (bufoff) + ldsw + _i * 8192), 16, 0, 0); } while (0)
; #define G_LDA(dst, b, h) do { _Pragma("unroll") for (int m = 0; m < 4; ++m) _Pragma("unroll") for (int k = 0; k < 2; ++k) dst[m][k] = *(const LAS bf16x8*)(lds + G_SA(b, h) + aoff + m * 2048 + k * 1024); } while (0)
; #define G_LDB(dst, b, h) do { _Pragma("unroll") for (int n = 0; n < 2; ++n) _Pragma("unroll") for (int k = 0; k < 2; ++k) dst[n][k] = *(const LAS bf16x8*)(lds + G_SB(b, h) + boff + n * 2048 + k * 1024); } while (0)
; #define G_MMA(ai, bj, At, Bt) do { __builtin_amdgcn_s_setprio(1); _Pragma("unroll") for (int m = 0; m < 4; ++m) _Pragma("unroll") for (int n = 0; n < 2; ++n) _Pragma("unroll") for (int k = 0; k < 2; ++k) \
;         acc[ai][bj][m][n] = __builtin_amdgcn_mfma_f32_16x16x32_bf16(Bt[n][k], At[m][k], acc[ai][bj][m][n], 0, 0, 0); __builtin_amdgcn_s_setprio(0); } while (0)
; #define G_WAIT_L(n) asm volatile("s_waitcnt lgkmcnt(" #n ")" ::: "memory")
; #define G_BAR __builtin_amdgcn_s_barrier()
; #define G_SCHED __builtin_amdgcn_sched_barrier(0)
; template <class J>
; DI void gemm_phase(LAS unsigned char* lds, const J& job) {
;     ...
;       const bool last = (t == nt - 2);
;       const char* a1 = cA + G_KT(t + 1);
;       const char* a2 = last ? nA + G_KT(0) : cA + G_KT(t + 2); const char* b2 = last ? nB + G_KT(0) : cB + G_KT(t + 2);
;       const char* a3 = last ? nA + G_KT(1) : cA + G_KT(t + 3); const char* b3 = last ? nB + G_KT(1) : cB + G_KT(t + 3);
;       G_LDB(B0, 0, 0); G_SCHED; G_LDA(At, 0, 0); G_STAGE(G_SA(1, 1), a1 + hstepA, voffA);
;       G_WAIT_L(8); G_BAR; G_WAIT_L(0); G_MMA(0, 0, At, B0); G_BAR; G_SCHED;
;       G_LDB(B1, 0, 1); G_STAGE(G_SB(0, 0), b2, voffB);
;       G_BAR; G_WAIT_L(0); G_MMA(0, 1, At, B1); G_BAR;
;       G_LDA(At, 0, 1); G_STAGE(G_SA(0, 0), a2, voffA);
;       G_BAR; G_WAIT_L(0); G_MMA(1, 0, At, B0); G_BAR; G_SCHED;
.LBB0_74:
	s_add_i32 s1, s56, 0xffffff80
	s_and_b32 s0, s7, 0xf80
	s_and_b32 s1, s1, 0xf00
	s_add_u32 s57, s68, s1
	s_addc_u32 s70, s69, 0
	s_add_u32 s1, s66, s1
	s_addc_u32 s71, s67, 0
	s_and_b32 s72, s56, 0xf80
	s_add_u32 s80, s68, s72
	s_addc_u32 s73, s69, 0
	s_add_u32 s38, s66, s72
	s_addc_u32 s2, s67, 0
	s_cmp_eq_u32 s6, 28
	s_cselect_b32 s75, s46, s70
	s_cselect_b32 s74, s45, s57
	s_cselect_b32 s77, vcc_lo, s71
	s_cselect_b32 s76, s47, s1
	s_cselect_b32 s73, s97, s73
	s_cselect_b32 s72, s33, s80
	s_cselect_b32 s71, s5, s2
	s_cselect_b32 s70, vcc_hi, s38
	s_add_i32 s2, s84, 0x100
	v_add_u32_e32 v100, s2, v248
	ds_read_b128 v[84:87], v100
	ds_read_b128 v[88:91], v100 offset:1024
	ds_read_b128 v[96:99], v100 offset:2048
	ds_read_b128 v[100:103], v100 offset:3072
	s_add_u32 s0, s19, s0
	s_addc_u32 s1, s21, 0
	s_add_i32 m0, s14, 0xc000
	ds_read_b128 v[154:157], v249
	ds_read_b128 v[158:161], v249 offset:1024
	ds_read_b128 v[162:165], v249 offset:2048
	ds_read_b128 v[166:169], v249 offset:3072
	ds_read_b128 v[170:173], v249 offset:4096
	ds_read_b128 v[174:177], v249 offset:5120
	ds_read_b128 v[178:181], v249 offset:6144
	ds_read_b128 v[182:185], v249 offset:7168
	global_load_lds_dwordx4 v148, s[0:1]
	s_add_i32 m0, s14, 0xe000
	s_nop 0
	global_load_lds_dwordx4 v150, s[0:1]
	s_waitcnt lgkmcnt(8)
	s_barrier
	s_waitcnt lgkmcnt(0)
	v_mfma_f32_16x16x32_bf16 v[140:143], v[84:87], v[154:157], v[140:143]
	v_mfma_f32_16x16x32_bf16 v[136:139], v[96:99], v[154:157], v[136:139]
	v_mfma_f32_16x16x32_bf16 v[124:127], v[84:87], v[162:165], v[124:127]
	v_mfma_f32_16x16x32_bf16 v[120:123], v[96:99], v[162:165], v[120:123]
	v_mfma_f32_16x16x32_bf16 v[108:111], v[84:87], v[170:173], v[108:111]
	v_mfma_f32_16x16x32_bf16 v[104:107], v[96:99], v[170:173], v[104:107]
	v_mfma_f32_16x16x32_bf16 v[76:79], v[84:87], v[178:181], v[76:79]
	v_mfma_f32_16x16x32_bf16 v[72:75], v[96:99], v[178:181], v[72:75]
	v_mfma_f32_16x16x32_bf16 v[140:143], v[88:91], v[158:161], v[140:143]
	v_mfma_f32_16x16x32_bf16 v[136:139], v[100:103], v[158:161], v[136:139]
	v_mfma_f32_16x16x32_bf16 v[124:127], v[88:91], v[166:169], v[124:127]
	v_mfma_f32_16x16x32_bf16 v[120:123], v[100:103], v[166:169], v[120:123]
	v_mfma_f32_16x16x32_bf16 v[108:111], v[88:91], v[174:177], v[108:111]
	v_mfma_f32_16x16x32_bf16 v[104:107], v[100:103], v[174:177], v[104:107]
	v_mfma_f32_16x16x32_bf16 v[76:79], v[88:91], v[182:185], v[76:79]
	v_mfma_f32_16x16x32_bf16 v[72:75], v[100:103], v[182:185], v[72:75]
	s_barrier
	s_add_i32 s38, s85, 0x100
	s_add_i32 s0, s2, s78
	v_add_u32_e32 v198, s38, v248
	s_mov_b32 m0, s0
	ds_read_b128 v[186:189], v198
	ds_read_b128 v[190:193], v198 offset:1024
	ds_read_b128 v[194:197], v198 offset:2048
	ds_read_b128 v[198:201], v198 offset:3072
	global_load_lds_dwordx4 v146, s[76:77]
	s_add_i32 m0, s0, 0x2000
	s_nop 0
	global_load_lds_dwordx4 v152, s[76:77]
	s_barrier
	s_waitcnt lgkmcnt(0)
	v_mfma_f32_16x16x32_bf16 v[132:135], v[186:189], v[154:157], v[132:135]
	v_mfma_f32_16x16x32_bf16 v[128:131], v[194:197], v[154:157], v[128:131]
	v_mfma_f32_16x16x32_bf16 v[116:119], v[186:189], v[162:165], v[116:119]
	v_mfma_f32_16x16x32_bf16 v[112:115], v[194:197], v[162:165], v[112:115]
	v_mfma_f32_16x16x32_bf16 v[92:95], v[186:189], v[170:173], v[92:95]
	v_mfma_f32_16x16x32_bf16 v[80:83], v[194:197], v[170:173], v[80:83]
	v_mfma_f32_16x16x32_bf16 v[68:71], v[186:189], v[178:181], v[68:71]
	v_mfma_f32_16x16x32_bf16 v[64:67], v[194:197], v[178:181], v[64:67]
	v_mfma_f32_16x16x32_bf16 v[132:135], v[190:193], v[158:161], v[132:135]
	v_mfma_f32_16x16x32_bf16 v[128:131], v[198:201], v[158:161], v[128:131]
	v_mfma_f32_16x16x32_bf16 v[116:119], v[190:193], v[166:169], v[116:119]
	v_mfma_f32_16x16x32_bf16 v[112:115], v[198:201], v[166:169], v[112:115]
	v_mfma_f32_16x16x32_bf16 v[92:95], v[190:193], v[174:177], v[92:95]
	v_mfma_f32_16x16x32_bf16 v[80:83], v[198:201], v[174:177], v[80:83]
	v_mfma_f32_16x16x32_bf16 v[68:71], v[190:193], v[182:185], v[68:71]
	v_mfma_f32_16x16x32_bf16 v[64:67], v[198:201], v[182:185], v[64:67]
	s_mov_b32 m0, s14
	s_barrier
	ds_read_b128 v[154:157], v249 offset:16384
	ds_read_b128 v[158:161], v249 offset:17408
	ds_read_b128 v[162:165], v249 offset:18432
	ds_read_b128 v[166:169], v249 offset:19456
	ds_read_b128 v[170:173], v249 offset:20480
	ds_read_b128 v[174:177], v249 offset:21504
	ds_read_b128 v[178:181], v249 offset:22528
	ds_read_b128 v[182:185], v249 offset:23552
	global_load_lds_dwordx4 v148, s[74:75]
	s_mov_b32 m0, s15
	s_nop 0
	global_load_lds_dwordx4 v150, s[74:75]
	s_barrier
	s_waitcnt lgkmcnt(0)
	v_mfma_f32_16x16x32_bf16 v[60:63], v[84:87], v[154:157], v[60:63]
	v_mfma_f32_16x16x32_bf16 v[56:59], v[96:99], v[154:157], v[56:59]
	v_mfma_f32_16x16x32_bf16 v[44:47], v[84:87], v[162:165], v[44:47]
	v_mfma_f32_16x16x32_bf16 v[40:43], v[96:99], v[162:165], v[40:43]
	v_mfma_f32_16x16x32_bf16 v[28:31], v[84:87], v[170:173], v[28:31]
	v_mfma_f32_16x16x32_bf16 v[24:27], v[96:99], v[170:173], v[24:27]
	v_mfma_f32_16x16x32_bf16 v[12:15], v[84:87], v[178:181], v[12:15]
	v_mfma_f32_16x16x32_bf16 v[8:11], v[96:99], v[178:181], v[8:11]
	v_mfma_f32_16x16x32_bf16 v[60:63], v[88:91], v[158:161], v[60:63]
	v_mfma_f32_16x16x32_bf16 v[56:59], v[100:103], v[158:161], v[56:59]
	v_mfma_f32_16x16x32_bf16 v[44:47], v[88:91], v[166:169], v[44:47]
	v_mfma_f32_16x16x32_bf16 v[40:43], v[100:103], v[166:169], v[40:43]
	v_mfma_f32_16x16x32_bf16 v[28:31], v[88:91], v[174:177], v[28:31]
	v_mfma_f32_16x16x32_bf16 v[24:27], v[100:103], v[174:177], v[24:27]
	v_mfma_f32_16x16x32_bf16 v[12:15], v[88:91], v[182:185], v[12:15]
	v_mfma_f32_16x16x32_bf16 v[8:11], v[100:103], v[182:185], v[8:11]
	s_barrier
; #define G_STAGE(bufoff, gbase, voff) do { _Pragma("unroll") for (int _i = 0; _i < 2; ++_i) \
;         __builtin_amdgcn_global_load_lds((const unsigned*)((const char*)(gbase) + (voff)[_i]), (LAS unsigned*)(lds + (bufoff) + ldsw + _i * 8192), 16, 0, 0); } while (0)
; #define G_LDA(dst, b, h) do { _Pragma("unroll") for (int m = 0; m < 4; ++m) _Pragma("unroll") for (int k = 0; k < 2; ++k) dst[m][k] = *(const LAS bf16x8*)(lds + G_SA(b, h) + aoff + m * 2048 + k * 1024); } while (0)
; #define G_LDB(dst, b, h) do { _Pragma("unroll") for (int n = 0; n < 2; ++n) _Pragma("unroll") for (int k = 0; k < 2; ++k) dst[n][k] = *(const LAS bf16x8*)(lds + G_SB(b, h) + boff + n * 2048 + k * 1024); } while (0)
; #define G_MMA(ai, bj, At, Bt) do { __builtin_amdgcn_s_setprio(1); _Pragma("unroll") for (int m = 0; m < 4; ++m) _Pragma("unroll") for (int n = 0; n < 2; ++n) _Pragma("unroll") for (int k = 0; k < 2; ++k) \
;         acc[ai][bj][m][n] = __builtin_amdgcn_mfma_f32_16x16x32_bf16(Bt[n][k], At[m][k], acc[ai][bj][m][n], 0, 0, 0); __builtin_amdgcn_s_setprio(0); } while (0)
; #define G_WAIT_V(n) asm volatile("s_waitcnt vmcnt(" #n ")" ::: "memory")
; #define G_WAIT_L(n) asm volatile("s_waitcnt lgkmcnt(" #n ")" ::: "memory")
; #define G_BAR __builtin_amdgcn_s_barrier()
; #define G_SCHED __builtin_amdgcn_sched_barrier(0)
; template <class J>
; DI void gemm_phase(LAS unsigned char* lds, const J& job) {
;     ...
;       G_STAGE(G_SB(0, 1), b2 + hstepB, voffB);
;       G_WAIT_V(6); G_BAR; G_MMA(1, 1, At, B1); G_BAR;
;       G_LDB(B0, 1, 0); G_SCHED; G_LDA(At, 1, 0); G_STAGE(G_SA(0, 1), a2 + hstepA, voffA);
;       G_WAIT_L(8); G_BAR; G_WAIT_L(0); G_MMA(0, 0, At, B0); G_BAR; G_SCHED;
;       G_LDB(B1, 1, 1); G_STAGE(G_SB(1, 0), b3, voffB);
;       G_BAR; G_WAIT_L(0); G_MMA(0, 1, At, B1); G_BAR;
;       G_LDA(At, 1, 1); G_STAGE(G_SA(1, 0), a3, voffA);
	s_add_u32 s0, s76, 0x1000000
	s_addc_u32 s1, s77, 0
	s_add_i32 s2, s38, s78
	s_mov_b32 m0, s2
	s_nop 0
	global_load_lds_dwordx4 v146, s[0:1]
	s_add_i32 m0, s2, 0x2000
	s_nop 0
	global_load_lds_dwordx4 v152, s[0:1]
	s_waitcnt vmcnt(6)
	s_barrier
	v_mfma_f32_16x16x32_bf16 v[52:55], v[186:189], v[154:157], v[52:55]
	v_mfma_f32_16x16x32_bf16 v[48:51], v[194:197], v[154:157], v[48:51]
	v_mfma_f32_16x16x32_bf16 v[36:39], v[186:189], v[162:165], v[36:39]
	v_mfma_f32_16x16x32_bf16 v[32:35], v[194:197], v[162:165], v[32:35]
	v_mfma_f32_16x16x32_bf16 v[20:23], v[186:189], v[170:173], v[20:23]
	v_mfma_f32_16x16x32_bf16 v[16:19], v[194:197], v[170:173], v[16:19]
	v_mfma_f32_16x16x32_bf16 v[4:7], v[186:189], v[178:181], v[4:7]
	v_mfma_f32_16x16x32_bf16 v[0:3], v[194:197], v[178:181], v[0:3]
	v_mfma_f32_16x16x32_bf16 v[52:55], v[190:193], v[158:161], v[52:55]
	v_mfma_f32_16x16x32_bf16 v[48:51], v[198:201], v[158:161], v[48:51]
	v_mfma_f32_16x16x32_bf16 v[36:39], v[190:193], v[166:169], v[36:39]
	v_mfma_f32_16x16x32_bf16 v[32:35], v[198:201], v[166:169], v[32:35]
	v_mfma_f32_16x16x32_bf16 v[20:23], v[190:193], v[174:177], v[20:23]
	v_mfma_f32_16x16x32_bf16 v[16:19], v[198:201], v[174:177], v[16:19]
	v_mfma_f32_16x16x32_bf16 v[4:7], v[190:193], v[182:185], v[4:7]
	v_mfma_f32_16x16x32_bf16 v[0:3], v[198:201], v[182:185], v[0:3]
	s_add_i32 s2, s88, 0x100
	v_add_u32_e32 v100, s2, v248
	s_barrier
	ds_read_b128 v[84:87], v100
	ds_read_b128 v[88:91], v100 offset:1024
	ds_read_b128 v[96:99], v100 offset:2048
	ds_read_b128 v[100:103], v100 offset:3072
	s_add_u32 s0, s74, 0x80000
	s_addc_u32 s1, s75, 0
	s_mov_b32 m0, s83
	ds_read_b128 v[154:157], v249 offset:32768
	ds_read_b128 v[158:161], v249 offset:33792
	ds_read_b128 v[162:165], v249 offset:34816
	ds_read_b128 v[166:169], v249 offset:35840
	ds_read_b128 v[170:173], v249 offset:36864
	ds_read_b128 v[174:177], v249 offset:37888
	ds_read_b128 v[178:181], v249 offset:38912
	ds_read_b128 v[182:185], v249 offset:39936
	global_load_lds_dwordx4 v148, s[0:1]
	s_mov_b32 m0, s36
	s_nop 0
	global_load_lds_dwordx4 v150, s[0:1]
	s_waitcnt lgkmcnt(8)
	s_barrier
	s_waitcnt lgkmcnt(0)
	v_mfma_f32_16x16x32_bf16 v[140:143], v[84:87], v[154:157], v[140:143]
	v_mfma_f32_16x16x32_bf16 v[136:139], v[96:99], v[154:157], v[136:139]
	v_mfma_f32_16x16x32_bf16 v[124:127], v[84:87], v[162:165], v[124:127]
	v_mfma_f32_16x16x32_bf16 v[120:123], v[96:99], v[162:165], v[120:123]
	v_mfma_f32_16x16x32_bf16 v[108:111], v[84:87], v[170:173], v[108:111]
	v_mfma_f32_16x16x32_bf16 v[104:107], v[96:99], v[170:173], v[104:107]
	v_mfma_f32_16x16x32_bf16 v[76:79], v[84:87], v[178:181], v[76:79]
	v_mfma_f32_16x16x32_bf16 v[72:75], v[96:99], v[178:181], v[72:75]
	v_mfma_f32_16x16x32_bf16 v[140:143], v[88:91], v[158:161], v[140:143]
	v_mfma_f32_16x16x32_bf16 v[136:139], v[100:103], v[158:161], v[136:139]
	v_mfma_f32_16x16x32_bf16 v[124:127], v[88:91], v[166:169], v[124:127]
	v_mfma_f32_16x16x32_bf16 v[120:123], v[100:103], v[166:169], v[120:123]
	v_mfma_f32_16x16x32_bf16 v[108:111], v[88:91], v[174:177], v[108:111]
	v_mfma_f32_16x16x32_bf16 v[104:107], v[100:103], v[174:177], v[104:107]
	v_mfma_f32_16x16x32_bf16 v[76:79], v[88:91], v[182:185], v[76:79]
	v_mfma_f32_16x16x32_bf16 v[72:75], v[100:103], v[182:185], v[72:75]
	s_barrier
	s_add_i32 s38, s89, 0x100
	s_add_i32 s0, s2, s78
	v_add_u32_e32 v198, s38, v248
	s_mov_b32 m0, s0
	ds_read_b128 v[186:189], v198
	ds_read_b128 v[190:193], v198 offset:1024
	ds_read_b128 v[194:197], v198 offset:2048
	ds_read_b128 v[198:201], v198 offset:3072
	global_load_lds_dwordx4 v146, s[70:71]
	s_add_i32 m0, s0, 0x2000
	s_nop 0
	global_load_lds_dwordx4 v152, s[70:71]
	s_barrier
	s_waitcnt lgkmcnt(0)
	v_mfma_f32_16x16x32_bf16 v[132:135], v[186:189], v[154:157], v[132:135]
	v_mfma_f32_16x16x32_bf16 v[128:131], v[194:197], v[154:157], v[128:131]
	v_mfma_f32_16x16x32_bf16 v[116:119], v[186:189], v[162:165], v[116:119]
	v_mfma_f32_16x16x32_bf16 v[112:115], v[194:197], v[162:165], v[112:115]
	v_mfma_f32_16x16x32_bf16 v[92:95], v[186:189], v[170:173], v[92:95]
	v_mfma_f32_16x16x32_bf16 v[80:83], v[194:197], v[170:173], v[80:83]
	v_mfma_f32_16x16x32_bf16 v[68:71], v[186:189], v[178:181], v[68:71]
	v_mfma_f32_16x16x32_bf16 v[64:67], v[194:197], v[178:181], v[64:67]
	v_mfma_f32_16x16x32_bf16 v[132:135], v[190:193], v[158:161], v[132:135]
	v_mfma_f32_16x16x32_bf16 v[128:131], v[198:201], v[158:161], v[128:131]
	v_mfma_f32_16x16x32_bf16 v[116:119], v[190:193], v[166:169], v[116:119]
	v_mfma_f32_16x16x32_bf16 v[112:115], v[198:201], v[166:169], v[112:115]
	v_mfma_f32_16x16x32_bf16 v[92:95], v[190:193], v[174:177], v[92:95]
	v_mfma_f32_16x16x32_bf16 v[80:83], v[198:201], v[174:177], v[80:83]
	v_mfma_f32_16x16x32_bf16 v[68:71], v[190:193], v[182:185], v[68:71]
	v_mfma_f32_16x16x32_bf16 v[64:67], v[198:201], v[182:185], v[64:67]
	s_mov_b32 m0, s24
	s_barrier
	ds_read_b128 v[154:157], v249 offset:49152
	ds_read_b128 v[158:161], v249 offset:50176
	ds_read_b128 v[162:165], v249 offset:51200
	ds_read_b128 v[166:169], v249 offset:52224
	ds_read_b128 v[170:173], v249 offset:53248
	ds_read_b128 v[174:177], v249 offset:54272
	ds_read_b128 v[178:181], v249 offset:55296
	ds_read_b128 v[182:185], v249 offset:56320
	global_load_lds_dwordx4 v148, s[72:73]
	s_mov_b32 m0, s25
	s_nop 0
	global_load_lds_dwordx4 v150, s[72:73]
	s_barrier
; #define G_STAGE(bufoff, gbase, voff) do { _Pragma("unroll") for (int _i = 0; _i < 2; ++_i) \
;         __builtin_amdgcn_global_load_lds((const unsigned*)((const char*)(gbase) + (voff)[_i]), (LAS unsigned*)(lds + (bufoff) + ldsw + _i * 8192), 16, 0, 0); } while (0)
; #define G_MMA(ai, bj, At, Bt) do { __builtin_amdgcn_s_setprio(1); _Pragma("unroll") for (int m = 0; m < 4; ++m) _Pragma("unroll") for (int n = 0; n < 2; ++n) _Pragma("unroll") for (int k = 0; k < 2; ++k) \
;         acc[ai][bj][m][n] = __builtin_amdgcn_mfma_f32_16x16x32_bf16(Bt[n][k], At[m][k], acc[ai][bj][m][n], 0, 0, 0); __builtin_amdgcn_s_setprio(0); } while (0)
; #define G_WAIT_V(n) asm volatile("s_waitcnt vmcnt(" #n ")" ::: "memory")
; #define G_WAIT_L(n) asm volatile("s_waitcnt lgkmcnt(" #n ")" ::: "memory")
; #define G_BAR __builtin_amdgcn_s_barrier()
; #define G_SCHED __builtin_amdgcn_sched_barrier(0)
; template <class J>
; DI void gemm_phase(LAS unsigned char* lds, const J& job) {
;     ...
;       G_BAR; G_WAIT_L(0); G_MMA(1, 0, At, B0); G_BAR; G_SCHED;
;       G_STAGE(G_SB(1, 1), b3 + hstepB, voffB);
;       G_WAIT_V(6); G_BAR; G_MMA(1, 1, At, B1); G_BAR;
	s_waitcnt lgkmcnt(0)
	v_mfma_f32_16x16x32_bf16 v[60:63], v[84:87], v[154:157], v[60:63]
	v_mfma_f32_16x16x32_bf16 v[56:59], v[96:99], v[154:157], v[56:59]
	v_mfma_f32_16x16x32_bf16 v[44:47], v[84:87], v[162:165], v[44:47]
	v_mfma_f32_16x16x32_bf16 v[40:43], v[96:99], v[162:165], v[40:43]
	v_mfma_f32_16x16x32_bf16 v[28:31], v[84:87], v[170:173], v[28:31]
	v_mfma_f32_16x16x32_bf16 v[24:27], v[96:99], v[170:173], v[24:27]
	v_mfma_f32_16x16x32_bf16 v[12:15], v[84:87], v[178:181], v[12:15]
	v_mfma_f32_16x16x32_bf16 v[8:11], v[96:99], v[178:181], v[8:11]
	v_mfma_f32_16x16x32_bf16 v[60:63], v[88:91], v[158:161], v[60:63]
	v_mfma_f32_16x16x32_bf16 v[56:59], v[100:103], v[158:161], v[56:59]
	v_mfma_f32_16x16x32_bf16 v[44:47], v[88:91], v[166:169], v[44:47]
	v_mfma_f32_16x16x32_bf16 v[40:43], v[100:103], v[166:169], v[40:43]
	v_mfma_f32_16x16x32_bf16 v[28:31], v[88:91], v[174:177], v[28:31]
	v_mfma_f32_16x16x32_bf16 v[24:27], v[100:103], v[174:177], v[24:27]
	v_mfma_f32_16x16x32_bf16 v[12:15], v[88:91], v[182:185], v[12:15]
	v_mfma_f32_16x16x32_bf16 v[8:11], v[100:103], v[182:185], v[8:11]
	s_barrier
	s_add_u32 s0, s70, 0x1000000
	s_addc_u32 s1, s71, 0
	s_add_i32 s2, s38, s78
	s_mov_b32 m0, s2
	s_nop 0
	global_load_lds_dwordx4 v146, s[0:1]
	s_add_i32 m0, s2, 0x2000
	s_nop 0
	global_load_lds_dwordx4 v152, s[0:1]
	s_waitcnt vmcnt(6)
	s_barrier
	v_mfma_f32_16x16x32_bf16 v[52:55], v[186:189], v[154:157], v[52:55]
	v_mfma_f32_16x16x32_bf16 v[48:51], v[194:197], v[154:157], v[48:51]
	v_mfma_f32_16x16x32_bf16 v[36:39], v[186:189], v[162:165], v[36:39]
	v_mfma_f32_16x16x32_bf16 v[32:35], v[194:197], v[162:165], v[32:35]
	v_mfma_f32_16x16x32_bf16 v[20:23], v[186:189], v[170:173], v[20:23]
	v_mfma_f32_16x16x32_bf16 v[16:19], v[194:197], v[170:173], v[16:19]
	v_mfma_f32_16x16x32_bf16 v[4:7], v[186:189], v[178:181], v[4:7]
	v_mfma_f32_16x16x32_bf16 v[0:3], v[194:197], v[178:181], v[0:3]
	v_mfma_f32_16x16x32_bf16 v[52:55], v[190:193], v[158:161], v[52:55]
	v_mfma_f32_16x16x32_bf16 v[48:51], v[198:201], v[158:161], v[48:51]
	v_mfma_f32_16x16x32_bf16 v[36:39], v[190:193], v[166:169], v[36:39]
	v_mfma_f32_16x16x32_bf16 v[32:35], v[198:201], v[166:169], v[32:35]
	v_mfma_f32_16x16x32_bf16 v[20:23], v[190:193], v[174:177], v[20:23]
	v_mfma_f32_16x16x32_bf16 v[16:19], v[198:201], v[174:177], v[16:19]
	v_mfma_f32_16x16x32_bf16 v[4:7], v[190:193], v[182:185], v[4:7]
	v_mfma_f32_16x16x32_bf16 v[0:3], v[198:201], v[182:185], v[0:3]
	s_add_i32 s6, s6, 2
	s_addk_i32 s56, 0x100
	s_addk_i32 s7, 0x100
	s_cmp_gt_u32 s6, 29
	s_barrier
	s_cbranch_scc0 .LBB0_74
;   DI void epi(const Acc& acc, const Unit& u, int wr, int wc, int fr, int fq) const {
;     const int cc = u.pn * 64 + 16 * wc + 4 * fq;
;     u32x2 zz[2][4][4];
; #pragma unroll
;     for (int ai = 0; ai < 2; ++ai)
; #pragma unroll
;       for (int m = 0; m < 4; ++m) {
;         const u16* zr = Z + (size_t)(u.pm * 256 + ai * HALF + wr * 64 + m * 16 + fr) * NGATE + cc;
; #pragma unroll
;         for (int br = 0; br < 4; ++br) zz[ai][m][br] = *(const u32x2*)(zr + br * 2048);
;       }
;     f32x4 bg[4];
; #pragma unroll
;     for (int br = 0; br < 4; ++br) bg[br] = *(const f32x4*)(bgate + br * 2048 + cc);
	v_mov_b32_e32 v84, v247
	v_mov_b32_e32 v85, v246
	s_lshl_b32 s0, s44, 6
	s_or_b32 s0, s0, s96
	v_lshl_add_u32 v84, v84, 2, s0
	s_lshl_b32 s0, s64, 8
	s_add_i32 s0, s0, s37
	v_add_u32_e32 v224, s0, v85
	v_ashrrev_i32_e32 v85, 31, v84
	v_lshlrev_b64 v[154:155], 1, v[84:85]
	v_ashrrev_i32_e32 v225, 31, v224
	v_lshl_add_u64 v[86:87], s[26:27], 0, v[154:155]
	v_lshlrev_b64 v[88:89], 14, v[224:225]
	v_lshl_add_u64 v[88:89], v[86:87], 0, v[88:89]
	v_add_co_u32_e32 v90, vcc, s82, v88
	v_add_u32_e32 v212, 16, v224
	s_nop 0
	v_addc_co_u32_e32 v91, vcc, 0, v89, vcc
	v_ashrrev_i32_e32 v213, 31, v212
	v_add_co_u32_e32 v96, vcc, s92, v88
	v_lshlrev_b64 v[98:99], 14, v[212:213]
	s_nop 0
	v_addc_co_u32_e32 v97, vcc, 0, v89, vcc
	v_lshl_add_u64 v[98:99], v[86:87], 0, v[98:99]
	v_add_co_u32_e32 v100, vcc, s82, v98
	v_add_u32_e32 v202, 32, v224
	s_nop 0
	v_addc_co_u32_e32 v101, vcc, 0, v99, vcc
	global_load_dwordx2 v[230:231], v[90:91], off offset:-4096
	global_load_dwordx2 v[226:227], v[90:91], off
	global_load_dwordx2 v[220:221], v[100:101], off offset:-4096
	global_load_dwordx2 v[214:215], v[100:101], off
	v_add_co_u32_e32 v90, vcc, s92, v98
	v_ashrrev_i32_e32 v203, 31, v202
	s_nop 0
	v_addc_co_u32_e32 v91, vcc, 0, v99, vcc
	global_load_dwordx2 v[232:233], v[88:89], off
	global_load_dwordx2 v[228:229], v[96:97], off
	global_load_dwordx2 v[222:223], v[98:99], off
	global_load_dwordx2 v[216:217], v[90:91], off
	v_lshlrev_b64 v[88:89], 14, v[202:203]
	v_lshl_add_u64 v[88:89], v[86:87], 0, v[88:89]
	v_add_co_u32_e32 v90, vcc, s82, v88
	v_add_u32_e32 v190, 48, v224
	s_nop 0
	v_addc_co_u32_e32 v91, vcc, 0, v89, vcc
	v_ashrrev_i32_e32 v191, 31, v190
	v_add_co_u32_e32 v96, vcc, s92, v88
	v_lshlrev_b64 v[98:99], 14, v[190:191]
	s_nop 0
	v_addc_co_u32_e32 v97, vcc, 0, v89, vcc
	v_lshl_add_u64 v[98:99], v[86:87], 0, v[98:99]
	v_add_co_u32_e32 v100, vcc, s82, v98
	v_add_u32_e32 v184, 0x80, v224
	s_nop 0
	v_addc_co_u32_e32 v101, vcc, 0, v99, vcc
	global_load_dwordx2 v[210:211], v[90:91], off offset:-4096
	global_load_dwordx2 v[206:207], v[90:91], off
	global_load_dwordx2 v[200:201], v[100:101], off offset:-4096
	global_load_dwordx2 v[192:193], v[100:101], off
	v_add_co_u32_e32 v90, vcc, s92, v98
	v_lshl_add_u64 v[84:85], v[84:85], 2, s[12:13]
	v_ashrrev_i32_e32 v185, 31, v184
	v_addc_co_u32_e32 v91, vcc, 0, v99, vcc
	global_load_dwordx4 v[100:103], v[84:85], off
	global_load_dwordx2 v[218:219], v[88:89], off
	global_load_dwordx2 v[208:209], v[96:97], off
	global_load_dwordx2 v[204:205], v[98:99], off
	global_load_dwordx2 v[198:199], v[90:91], off
	v_lshlrev_b64 v[88:89], 14, v[184:185]
	v_lshl_add_u64 v[88:89], v[86:87], 0, v[88:89]
	v_add_co_u32_e32 v90, vcc, s82, v88
	v_add_u32_e32 v174, 0x90, v224
	s_nop 0
	v_addc_co_u32_e32 v91, vcc, 0, v89, vcc
	v_add_co_u32_e32 v156, vcc, s92, v88
	v_ashrrev_i32_e32 v175, 31, v174
	s_nop 0
	v_addc_co_u32_e32 v157, vcc, 0, v89, vcc
	v_add_co_u32_e32 v96, vcc, s82, v84
	v_lshlrev_b64 v[158:159], 14, v[174:175]
	s_nop 0
	v_addc_co_u32_e32 v97, vcc, 0, v85, vcc
	global_load_dwordx4 v[96:99], v[96:97], off
	v_lshl_add_u64 v[158:159], v[86:87], 0, v[158:159]
	v_add_co_u32_e32 v160, vcc, s82, v158
	v_add_u32_e32 v164, 0xa0, v224
	s_nop 0
	v_addc_co_u32_e32 v161, vcc, 0, v159, vcc
	global_load_dwordx2 v[194:195], v[90:91], off offset:-4096
	global_load_dwordx2 v[186:187], v[90:91], off
	global_load_dwordx2 v[180:181], v[160:161], off offset:-4096
	global_load_dwordx2 v[176:177], v[160:161], off
	v_add_co_u32_e32 v90, vcc, s92, v158
	v_ashrrev_i32_e32 v165, 31, v164
	s_nop 0
	v_addc_co_u32_e32 v91, vcc, 0, v159, vcc
	global_load_dwordx2 v[196:197], v[88:89], off
	global_load_dwordx2 v[188:189], v[156:157], off
	global_load_dwordx2 v[182:183], v[158:159], off
	global_load_dwordx2 v[178:179], v[90:91], off
	v_lshlrev_b64 v[88:89], 14, v[164:165]
	v_lshl_add_u64 v[162:163], v[86:87], 0, v[88:89]
	v_add_co_u32_e32 v158, vcc, s82, v162
	v_add_u32_e32 v156, 0xb0, v224
	s_nop 0
	v_addc_co_u32_e32 v159, vcc, 0, v163, vcc
	v_add_co_u32_e32 v168, vcc, s92, v162
	v_ashrrev_i32_e32 v157, 31, v156
	s_nop 0
	v_addc_co_u32_e32 v169, vcc, 0, v163, vcc
	v_add_co_u32_e32 v88, vcc, s54, v84
	v_lshlrev_b64 v[160:161], 14, v[156:157]
	s_nop 0
	v_addc_co_u32_e32 v89, vcc, 0, v85, vcc
	global_load_dwordx4 v[88:91], v[88:89], off
	v_lshl_add_u64 v[250:251], v[86:87], 0, v[160:161]
	v_add_co_u32_e32 v86, vcc, s82, v250
	s_mov_b32 s44, s20
	s_nop 0
	v_addc_co_u32_e32 v87, vcc, 0, v251, vcc
	v_add_co_u32_e32 v84, vcc, s55, v84
	global_load_dwordx2 v[170:171], v[158:159], off offset:-4096
	global_load_dwordx2 v[166:167], v[158:159], off
	global_load_dwordx2 v[160:161], v[86:87], off offset:-4096
	s_nop 0
	global_load_dwordx2 v[158:159], v[86:87], off
	v_addc_co_u32_e32 v85, vcc, 0, v85, vcc
	global_load_dwordx4 v[84:87], v[84:85], off
	v_add_co_u32_e32 v252, vcc, s92, v250
	s_mov_b32 s64, s18
	s_nop 0
	v_addc_co_u32_e32 v253, vcc, 0, v251, vcc
	s_and_b64 vcc, exec, s[8:9]
	s_mov_b64 s[66:67], s[62:63]
	s_mov_b64 s[68:69], s[22:23]
	v_readlane_b32 s0, v255, 23
	s_cmpk_gt_u32 s0, 0xff
	s_cbranch_scc1 .Lds_gate_x
	s_barrier

; #define G_STAGE(bufoff, gbase, voff) do { _Pragma("unroll") for (int _i = 0; _i < 2; ++_i) \
;         __builtin_amdgcn_global_load_lds((const unsigned*)((const char*)(gbase) + (voff)[_i]), (LAS unsigned*)(lds + (bufoff) + ldsw + _i * 8192), 16, 0, 0); } while (0)
; #define G_LDA(dst, b, h) do { _Pragma("unroll") for (int m = 0; m < 4; ++m) _Pragma("unroll") for (int k = 0; k < 2; ++k) dst[m][k] = *(const LAS bf16x8*)(lds + G_SA(b, h) + aoff + m * 2048 + k * 1024); } while (0)
; #define G_LDB(dst, b, h) do { _Pragma("unroll") for (int n = 0; n < 2; ++n) _Pragma("unroll") for (int k = 0; k < 2; ++k) dst[n][k] = *(const LAS bf16x8*)(lds + G_SB(b, h) + boff + n * 2048 + k * 1024); } while (0)
; #define G_MMA(ai, bj, At, Bt) do { __builtin_amdgcn_s_setprio(1); _Pragma("unroll") for (int m = 0; m < 4; ++m) _Pragma("unroll") for (int n = 0; n < 2; ++n) _Pragma("unroll") for (int k = 0; k < 2; ++k) \
;         acc[ai][bj][m][n] = __builtin_amdgcn_mfma_f32_16x16x32_bf16(Bt[n][k], At[m][k], acc[ai][bj][m][n], 0, 0, 0); __builtin_amdgcn_s_setprio(0); } while (0)
; #define G_WAIT_L(n) asm volatile("s_waitcnt lgkmcnt(" #n ")" ::: "memory")
; #define G_BAR __builtin_amdgcn_s_barrier()
; #define G_SCHED __builtin_amdgcn_sched_barrier(0)
; template <class J>
; DI void gemm_phase(LAS unsigned char* lds, const J& job) {
;     ...
;       const bool last = (t == nt - 2);
;       const char* a1 = cA + G_KT(t + 1);
;       const char* a2 = last ? nA + G_KT(0) : cA + G_KT(t + 2); const char* b2 = last ? nB + G_KT(0) : cB + G_KT(t + 2);
;       const char* a3 = last ? nA + G_KT(1) : cA + G_KT(t + 3); const char* b3 = last ? nB + G_KT(1) : cB + G_KT(t + 3);
;       G_LDB(B0, 0, 0); G_SCHED; G_LDA(At, 0, 0); G_STAGE(G_SA(1, 1), a1 + hstepA, voffA);
;       G_WAIT_L(8); G_BAR; G_WAIT_L(0); G_MMA(0, 0, At, B0); G_BAR; G_SCHED;
;       G_LDB(B1, 0, 1); G_STAGE(G_SB(0, 0), b2, voffB);
;       G_BAR; G_WAIT_L(0); G_MMA(0, 1, At, B1); G_BAR;
;       G_LDA(At, 0, 1); G_STAGE(G_SA(0, 0), a2, voffA);
;       G_BAR; G_WAIT_L(0); G_MMA(1, 0, At, B0); G_BAR; G_SCHED;
.LBB0_104:
	s_add_i32 s1, s56, 0xffffff80
	s_and_b32 s0, s7, 0x380
	s_and_b32 s1, s1, 0x380
	s_add_u32 s57, s64, s1
	s_addc_u32 s66, s65, 0
	s_add_u32 s1, s62, s1
	s_addc_u32 s67, s63, 0
	s_and_b32 s68, s56, 0x380
	s_add_u32 s80, s64, s68
	s_addc_u32 s69, s65, 0
	s_add_u32 s97, s62, s68
	s_addc_u32 vcc_lo, s63, 0
	s_cmp_eq_u32 s6, 4
	s_cselect_b32 s71, s83, s66
	s_cselect_b32 s70, s47, s57
	s_cselect_b32 s73, s87, s67
	s_cselect_b32 s72, s86, s1
	s_cselect_b32 s69, s94, s69
	s_cselect_b32 s68, s33, s80
	s_cselect_b32 s67, s5, vcc_lo
	s_cselect_b32 s66, s96, s97
	s_add_i32 s1, s84, 0x100
	v_add_u32_e32 v134, s1, v138
	ds_read_b128 v[140:143], v134
	ds_read_b128 v[148:151], v134 offset:1024
	ds_read_b128 v[152:155], v134 offset:2048
	ds_read_b128 v[156:159], v134 offset:3072
	s_add_u32 vcc_lo, s9, s0
	s_addc_u32 vcc_hi, s17, 0
	s_add_i32 m0, s25, 0xc000
	ds_read_b128 v[160:163], v139
	ds_read_b128 v[164:167], v139 offset:1024
	ds_read_b128 v[168:171], v139 offset:2048
	ds_read_b128 v[172:175], v139 offset:3072
	ds_read_b128 v[176:179], v139 offset:4096
	ds_read_b128 v[180:183], v139 offset:5120
	ds_read_b128 v[184:187], v139 offset:6144
	ds_read_b128 v[188:191], v139 offset:7168
	global_load_lds_dwordx4 v132, vcc
	s_add_i32 m0, s25, 0xe000
	s_nop 0
	global_load_lds_dwordx4 v130, vcc
	s_waitcnt lgkmcnt(8)
	s_barrier
	s_waitcnt lgkmcnt(0)
	v_mfma_f32_16x16x32_bf16 v[124:127], v[140:143], v[160:163], v[124:127]
	v_mfma_f32_16x16x32_bf16 v[120:123], v[152:155], v[160:163], v[120:123]
	v_mfma_f32_16x16x32_bf16 v[116:119], v[140:143], v[168:171], v[116:119]
	v_mfma_f32_16x16x32_bf16 v[108:111], v[152:155], v[168:171], v[108:111]
	v_mfma_f32_16x16x32_bf16 v[100:103], v[140:143], v[176:179], v[100:103]
	v_mfma_f32_16x16x32_bf16 v[92:95], v[152:155], v[176:179], v[92:95]
	v_mfma_f32_16x16x32_bf16 v[84:87], v[140:143], v[184:187], v[84:87]
	v_mfma_f32_16x16x32_bf16 v[76:79], v[152:155], v[184:187], v[76:79]
	v_mfma_f32_16x16x32_bf16 v[124:127], v[148:151], v[164:167], v[124:127]
	v_mfma_f32_16x16x32_bf16 v[120:123], v[156:159], v[164:167], v[120:123]
	v_mfma_f32_16x16x32_bf16 v[116:119], v[148:151], v[172:175], v[116:119]
	v_mfma_f32_16x16x32_bf16 v[108:111], v[156:159], v[172:175], v[108:111]
	v_mfma_f32_16x16x32_bf16 v[100:103], v[148:151], v[180:183], v[100:103]
	v_mfma_f32_16x16x32_bf16 v[92:95], v[156:159], v[180:183], v[92:95]
	v_mfma_f32_16x16x32_bf16 v[84:87], v[148:151], v[188:191], v[84:87]
	v_mfma_f32_16x16x32_bf16 v[76:79], v[156:159], v[188:191], v[76:79]
	s_barrier
	s_add_i32 s0, s85, 0x100
	v_add_u32_e32 v134, s0, v138
	s_add_i32 s1, s1, s24
	ds_read_b128 v[192:195], v134
	ds_read_b128 v[196:199], v134 offset:1024
	ds_read_b128 v[200:203], v134 offset:2048
	ds_read_b128 v[204:207], v134 offset:3072
	s_mov_b32 m0, s1
	s_nop 0
	global_load_lds_dwordx4 v146, s[72:73]
	s_add_i32 m0, s1, 0x2000
	s_nop 0
	global_load_lds_dwordx4 v128, s[72:73]
	s_barrier
	s_waitcnt lgkmcnt(0)
	v_mfma_f32_16x16x32_bf16 v[112:115], v[192:195], v[160:163], v[112:115]
	v_mfma_f32_16x16x32_bf16 v[104:107], v[200:203], v[160:163], v[104:107]
	v_mfma_f32_16x16x32_bf16 v[96:99], v[192:195], v[168:171], v[96:99]
	v_mfma_f32_16x16x32_bf16 v[88:91], v[200:203], v[168:171], v[88:91]
	v_mfma_f32_16x16x32_bf16 v[80:83], v[192:195], v[176:179], v[80:83]
	v_mfma_f32_16x16x32_bf16 v[72:75], v[200:203], v[176:179], v[72:75]
	v_mfma_f32_16x16x32_bf16 v[68:71], v[192:195], v[184:187], v[68:71]
	v_mfma_f32_16x16x32_bf16 v[64:67], v[200:203], v[184:187], v[64:67]
	v_mfma_f32_16x16x32_bf16 v[112:115], v[196:199], v[164:167], v[112:115]
	v_mfma_f32_16x16x32_bf16 v[104:107], v[204:207], v[164:167], v[104:107]
	v_mfma_f32_16x16x32_bf16 v[96:99], v[196:199], v[172:175], v[96:99]
	v_mfma_f32_16x16x32_bf16 v[88:91], v[204:207], v[172:175], v[88:91]
	v_mfma_f32_16x16x32_bf16 v[80:83], v[196:199], v[180:183], v[80:83]
	v_mfma_f32_16x16x32_bf16 v[72:75], v[204:207], v[180:183], v[72:75]
	v_mfma_f32_16x16x32_bf16 v[68:71], v[196:199], v[188:191], v[68:71]
	v_mfma_f32_16x16x32_bf16 v[64:67], v[204:207], v[188:191], v[64:67]
	s_mov_b32 m0, s25
	s_barrier
	ds_read_b128 v[160:163], v139 offset:16384
	ds_read_b128 v[164:167], v139 offset:17408
	ds_read_b128 v[168:171], v139 offset:18432
	ds_read_b128 v[172:175], v139 offset:19456
	ds_read_b128 v[176:179], v139 offset:20480
	ds_read_b128 v[180:183], v139 offset:21504
	ds_read_b128 v[184:187], v139 offset:22528
	ds_read_b128 v[188:191], v139 offset:23552
	global_load_lds_dwordx4 v132, s[70:71]
	s_mov_b32 m0, s36
	s_nop 0
	global_load_lds_dwordx4 v130, s[70:71]
	s_barrier
	s_waitcnt lgkmcnt(0)
	v_mfma_f32_16x16x32_bf16 v[60:63], v[140:143], v[160:163], v[60:63]
	v_mfma_f32_16x16x32_bf16 v[56:59], v[152:155], v[160:163], v[56:59]
	v_mfma_f32_16x16x32_bf16 v[52:55], v[140:143], v[168:171], v[52:55]
	v_mfma_f32_16x16x32_bf16 v[44:47], v[152:155], v[168:171], v[44:47]
	v_mfma_f32_16x16x32_bf16 v[36:39], v[140:143], v[176:179], v[36:39]
	v_mfma_f32_16x16x32_bf16 v[28:31], v[152:155], v[176:179], v[28:31]
	v_mfma_f32_16x16x32_bf16 v[20:23], v[140:143], v[184:187], v[20:23]
	v_mfma_f32_16x16x32_bf16 v[12:15], v[152:155], v[184:187], v[12:15]
	v_mfma_f32_16x16x32_bf16 v[60:63], v[148:151], v[164:167], v[60:63]
	v_mfma_f32_16x16x32_bf16 v[56:59], v[156:159], v[164:167], v[56:59]
	v_mfma_f32_16x16x32_bf16 v[52:55], v[148:151], v[172:175], v[52:55]
	v_mfma_f32_16x16x32_bf16 v[44:47], v[156:159], v[172:175], v[44:47]
	v_mfma_f32_16x16x32_bf16 v[36:39], v[148:151], v[180:183], v[36:39]
	v_mfma_f32_16x16x32_bf16 v[28:31], v[156:159], v[180:183], v[28:31]
	v_mfma_f32_16x16x32_bf16 v[20:23], v[148:151], v[188:191], v[20:23]
	v_mfma_f32_16x16x32_bf16 v[12:15], v[156:159], v[188:191], v[12:15]
	s_barrier
; #define G_STAGE(bufoff, gbase, voff) do { _Pragma("unroll") for (int _i = 0; _i < 2; ++_i) \
;         __builtin_amdgcn_global_load_lds((const unsigned*)((const char*)(gbase) + (voff)[_i]), (LAS unsigned*)(lds + (bufoff) + ldsw + _i * 8192), 16, 0, 0); } while (0)
; #define G_LDA(dst, b, h) do { _Pragma("unroll") for (int m = 0; m < 4; ++m) _Pragma("unroll") for (int k = 0; k < 2; ++k) dst[m][k] = *(const LAS bf16x8*)(lds + G_SA(b, h) + aoff + m * 2048 + k * 1024); } while (0)
; #define G_LDB(dst, b, h) do { _Pragma("unroll") for (int n = 0; n < 2; ++n) _Pragma("unroll") for (int k = 0; k < 2; ++k) dst[n][k] = *(const LAS bf16x8*)(lds + G_SB(b, h) + boff + n * 2048 + k * 1024); } while (0)
; #define G_MMA(ai, bj, At, Bt) do { __builtin_amdgcn_s_setprio(1); _Pragma("unroll") for (int m = 0; m < 4; ++m) _Pragma("unroll") for (int n = 0; n < 2; ++n) _Pragma("unroll") for (int k = 0; k < 2; ++k) \
;         acc[ai][bj][m][n] = __builtin_amdgcn_mfma_f32_16x16x32_bf16(Bt[n][k], At[m][k], acc[ai][bj][m][n], 0, 0, 0); __builtin_amdgcn_s_setprio(0); } while (0)
; #define G_WAIT_V(n) asm volatile("s_waitcnt vmcnt(" #n ")" ::: "memory")
; #define G_WAIT_L(n) asm volatile("s_waitcnt lgkmcnt(" #n ")" ::: "memory")
; #define G_BAR __builtin_amdgcn_s_barrier()
; #define G_SCHED __builtin_amdgcn_sched_barrier(0)
; template <class J>
; DI void gemm_phase(LAS unsigned char* lds, const J& job) {
;     ...
;       G_STAGE(G_SB(0, 1), b2 + hstepB, voffB);
;       G_WAIT_V(6); G_BAR; G_MMA(1, 1, At, B1); G_BAR;
;       G_LDB(B0, 1, 0); G_SCHED; G_LDA(At, 1, 0); G_STAGE(G_SA(0, 1), a2 + hstepA, voffA);
;       G_WAIT_L(8); G_BAR; G_WAIT_L(0); G_MMA(0, 0, At, B0); G_BAR; G_SCHED;
;       G_LDB(B1, 1, 1); G_STAGE(G_SB(1, 0), b3, voffB);
;       G_BAR; G_WAIT_L(0); G_MMA(0, 1, At, B1); G_BAR;
;       G_LDA(At, 1, 1); G_STAGE(G_SA(1, 0), a3, voffA);
	s_add_u32 s72, s72, 0x20000
	s_addc_u32 s73, s73, 0
	s_add_i32 s0, s0, s24
	s_mov_b32 m0, s0
	s_nop 0
	global_load_lds_dwordx4 v146, s[72:73]
	s_add_i32 m0, s0, 0x2000
	s_nop 0
	global_load_lds_dwordx4 v128, s[72:73]
	s_waitcnt vmcnt(6)
	s_barrier
	v_mfma_f32_16x16x32_bf16 v[48:51], v[192:195], v[160:163], v[48:51]
	v_mfma_f32_16x16x32_bf16 v[40:43], v[200:203], v[160:163], v[40:43]
	v_mfma_f32_16x16x32_bf16 v[32:35], v[192:195], v[168:171], v[32:35]
	v_mfma_f32_16x16x32_bf16 v[24:27], v[200:203], v[168:171], v[24:27]
	v_mfma_f32_16x16x32_bf16 v[16:19], v[192:195], v[176:179], v[16:19]
	v_mfma_f32_16x16x32_bf16 v[8:11], v[200:203], v[176:179], v[8:11]
	v_mfma_f32_16x16x32_bf16 v[4:7], v[192:195], v[184:187], v[4:7]
	v_mfma_f32_16x16x32_bf16 v[0:3], v[200:203], v[184:187], v[0:3]
	v_mfma_f32_16x16x32_bf16 v[48:51], v[196:199], v[164:167], v[48:51]
	v_mfma_f32_16x16x32_bf16 v[40:43], v[204:207], v[164:167], v[40:43]
	v_mfma_f32_16x16x32_bf16 v[32:35], v[196:199], v[172:175], v[32:35]
	v_mfma_f32_16x16x32_bf16 v[24:27], v[204:207], v[172:175], v[24:27]
	v_mfma_f32_16x16x32_bf16 v[16:19], v[196:199], v[180:183], v[16:19]
	v_mfma_f32_16x16x32_bf16 v[8:11], v[204:207], v[180:183], v[8:11]
	v_mfma_f32_16x16x32_bf16 v[4:7], v[196:199], v[188:191], v[4:7]
	v_mfma_f32_16x16x32_bf16 v[0:3], v[204:207], v[188:191], v[0:3]
	s_add_i32 s0, s88, 0x100
	v_add_u32_e32 v134, s0, v138
	s_barrier
	ds_read_b128 v[140:143], v134
	ds_read_b128 v[148:151], v134 offset:1024
	ds_read_b128 v[152:155], v134 offset:2048
	ds_read_b128 v[156:159], v134 offset:3072
	s_add_u32 s70, s70, 0x80000
	s_addc_u32 s71, s71, 0
	s_mov_b32 m0, s37
	ds_read_b128 v[160:163], v139 offset:32768
	ds_read_b128 v[164:167], v139 offset:33792
	ds_read_b128 v[168:171], v139 offset:34816
	ds_read_b128 v[172:175], v139 offset:35840
	ds_read_b128 v[176:179], v139 offset:36864
	ds_read_b128 v[180:183], v139 offset:37888
	ds_read_b128 v[184:187], v139 offset:38912
	ds_read_b128 v[188:191], v139 offset:39936
	global_load_lds_dwordx4 v132, s[70:71]
	s_mov_b32 m0, s38
	s_nop 0
	global_load_lds_dwordx4 v130, s[70:71]
	s_waitcnt lgkmcnt(8)
	s_barrier
	s_waitcnt lgkmcnt(0)
	v_mfma_f32_16x16x32_bf16 v[124:127], v[140:143], v[160:163], v[124:127]
	v_mfma_f32_16x16x32_bf16 v[120:123], v[152:155], v[160:163], v[120:123]
	v_mfma_f32_16x16x32_bf16 v[116:119], v[140:143], v[168:171], v[116:119]
	v_mfma_f32_16x16x32_bf16 v[108:111], v[152:155], v[168:171], v[108:111]
	v_mfma_f32_16x16x32_bf16 v[100:103], v[140:143], v[176:179], v[100:103]
	v_mfma_f32_16x16x32_bf16 v[92:95], v[152:155], v[176:179], v[92:95]
	v_mfma_f32_16x16x32_bf16 v[84:87], v[140:143], v[184:187], v[84:87]
	v_mfma_f32_16x16x32_bf16 v[76:79], v[152:155], v[184:187], v[76:79]
	v_mfma_f32_16x16x32_bf16 v[124:127], v[148:151], v[164:167], v[124:127]
	v_mfma_f32_16x16x32_bf16 v[120:123], v[156:159], v[164:167], v[120:123]
	v_mfma_f32_16x16x32_bf16 v[116:119], v[148:151], v[172:175], v[116:119]
	v_mfma_f32_16x16x32_bf16 v[108:111], v[156:159], v[172:175], v[108:111]
	v_mfma_f32_16x16x32_bf16 v[100:103], v[148:151], v[180:183], v[100:103]
	v_mfma_f32_16x16x32_bf16 v[92:95], v[156:159], v[180:183], v[92:95]
	v_mfma_f32_16x16x32_bf16 v[84:87], v[148:151], v[188:191], v[84:87]
	v_mfma_f32_16x16x32_bf16 v[76:79], v[156:159], v[188:191], v[76:79]
	s_barrier
	s_add_i32 s1, s89, 0x100
	v_add_u32_e32 v134, s1, v138
	s_add_i32 s0, s0, s24
	ds_read_b128 v[192:195], v134
	ds_read_b128 v[196:199], v134 offset:1024
	ds_read_b128 v[200:203], v134 offset:2048
	ds_read_b128 v[204:207], v134 offset:3072
	s_mov_b32 m0, s0
	s_nop 0
	global_load_lds_dwordx4 v146, s[66:67]
	s_add_i32 m0, s0, 0x2000
	s_nop 0
	global_load_lds_dwordx4 v128, s[66:67]
	s_barrier
	s_waitcnt lgkmcnt(0)
	v_mfma_f32_16x16x32_bf16 v[112:115], v[192:195], v[160:163], v[112:115]
	v_mfma_f32_16x16x32_bf16 v[104:107], v[200:203], v[160:163], v[104:107]
	v_mfma_f32_16x16x32_bf16 v[96:99], v[192:195], v[168:171], v[96:99]
	v_mfma_f32_16x16x32_bf16 v[88:91], v[200:203], v[168:171], v[88:91]
	v_mfma_f32_16x16x32_bf16 v[80:83], v[192:195], v[176:179], v[80:83]
	v_mfma_f32_16x16x32_bf16 v[72:75], v[200:203], v[176:179], v[72:75]
	v_mfma_f32_16x16x32_bf16 v[68:71], v[192:195], v[184:187], v[68:71]
	v_mfma_f32_16x16x32_bf16 v[64:67], v[200:203], v[184:187], v[64:67]
	v_mfma_f32_16x16x32_bf16 v[112:115], v[196:199], v[164:167], v[112:115]
	v_mfma_f32_16x16x32_bf16 v[104:107], v[204:207], v[164:167], v[104:107]
	v_mfma_f32_16x16x32_bf16 v[96:99], v[196:199], v[172:175], v[96:99]
	v_mfma_f32_16x16x32_bf16 v[88:91], v[204:207], v[172:175], v[88:91]
	v_mfma_f32_16x16x32_bf16 v[80:83], v[196:199], v[180:183], v[80:83]
	v_mfma_f32_16x16x32_bf16 v[72:75], v[204:207], v[180:183], v[72:75]
	v_mfma_f32_16x16x32_bf16 v[68:71], v[196:199], v[188:191], v[68:71]
	v_mfma_f32_16x16x32_bf16 v[64:67], v[204:207], v[188:191], v[64:67]
	s_mov_b32 m0, s75
	s_barrier
	ds_read_b128 v[160:163], v139 offset:49152
	ds_read_b128 v[164:167], v139 offset:50176
	ds_read_b128 v[168:171], v139 offset:51200
	ds_read_b128 v[172:175], v139 offset:52224
	ds_read_b128 v[176:179], v139 offset:53248
	ds_read_b128 v[180:183], v139 offset:54272
	ds_read_b128 v[184:187], v139 offset:55296
	ds_read_b128 v[188:191], v139 offset:56320
	global_load_lds_dwordx4 v132, s[68:69]
	s_mov_b32 m0, s76
	s_nop 0
	global_load_lds_dwordx4 v130, s[68:69]
	s_barrier
; #define G_STAGE(bufoff, gbase, voff) do { _Pragma("unroll") for (int _i = 0; _i < 2; ++_i) \
;         __builtin_amdgcn_global_load_lds((const unsigned*)((const char*)(gbase) + (voff)[_i]), (LAS unsigned*)(lds + (bufoff) + ldsw + _i * 8192), 16, 0, 0); } while (0)
; #define G_MMA(ai, bj, At, Bt) do { __builtin_amdgcn_s_setprio(1); _Pragma("unroll") for (int m = 0; m < 4; ++m) _Pragma("unroll") for (int n = 0; n < 2; ++n) _Pragma("unroll") for (int k = 0; k < 2; ++k) \
;         acc[ai][bj][m][n] = __builtin_amdgcn_mfma_f32_16x16x32_bf16(Bt[n][k], At[m][k], acc[ai][bj][m][n], 0, 0, 0); __builtin_amdgcn_s_setprio(0); } while (0)
; #define G_WAIT_V(n) asm volatile("s_waitcnt vmcnt(" #n ")" ::: "memory")
; #define G_WAIT_L(n) asm volatile("s_waitcnt lgkmcnt(" #n ")" ::: "memory")
; #define G_BAR __builtin_amdgcn_s_barrier()
; #define G_SCHED __builtin_amdgcn_sched_barrier(0)
; template <class J>
; DI void gemm_phase(LAS unsigned char* lds, const J& job) {
;     ...
;       G_BAR; G_WAIT_L(0); G_MMA(1, 0, At, B0); G_BAR; G_SCHED;
;       G_STAGE(G_SB(1, 1), b3 + hstepB, voffB);
;       G_WAIT_V(6); G_BAR; G_MMA(1, 1, At, B1); G_BAR;
	s_waitcnt lgkmcnt(0)
	v_mfma_f32_16x16x32_bf16 v[60:63], v[140:143], v[160:163], v[60:63]
	v_mfma_f32_16x16x32_bf16 v[56:59], v[152:155], v[160:163], v[56:59]
	v_mfma_f32_16x16x32_bf16 v[52:55], v[140:143], v[168:171], v[52:55]
	v_mfma_f32_16x16x32_bf16 v[44:47], v[152:155], v[168:171], v[44:47]
	v_mfma_f32_16x16x32_bf16 v[36:39], v[140:143], v[176:179], v[36:39]
	v_mfma_f32_16x16x32_bf16 v[28:31], v[152:155], v[176:179], v[28:31]
	v_mfma_f32_16x16x32_bf16 v[20:23], v[140:143], v[184:187], v[20:23]
	v_mfma_f32_16x16x32_bf16 v[12:15], v[152:155], v[184:187], v[12:15]
	v_mfma_f32_16x16x32_bf16 v[60:63], v[148:151], v[164:167], v[60:63]
	v_mfma_f32_16x16x32_bf16 v[56:59], v[156:159], v[164:167], v[56:59]
	v_mfma_f32_16x16x32_bf16 v[52:55], v[148:151], v[172:175], v[52:55]
	v_mfma_f32_16x16x32_bf16 v[44:47], v[156:159], v[172:175], v[44:47]
	v_mfma_f32_16x16x32_bf16 v[36:39], v[148:151], v[180:183], v[36:39]
	v_mfma_f32_16x16x32_bf16 v[28:31], v[156:159], v[180:183], v[28:31]
	v_mfma_f32_16x16x32_bf16 v[20:23], v[148:151], v[188:191], v[20:23]
	v_mfma_f32_16x16x32_bf16 v[12:15], v[156:159], v[188:191], v[12:15]
	s_barrier
	s_add_u32 s66, s66, 0x20000
	s_addc_u32 s67, s67, 0
	s_add_i32 s0, s1, s24
	s_mov_b32 m0, s0
	s_nop 0
	global_load_lds_dwordx4 v146, s[66:67]
	s_add_i32 m0, s0, 0x2000
	s_nop 0
	global_load_lds_dwordx4 v128, s[66:67]
	s_waitcnt vmcnt(6)
	s_barrier
	v_mfma_f32_16x16x32_bf16 v[48:51], v[192:195], v[160:163], v[48:51]
	v_mfma_f32_16x16x32_bf16 v[40:43], v[200:203], v[160:163], v[40:43]
	v_mfma_f32_16x16x32_bf16 v[32:35], v[192:195], v[168:171], v[32:35]
	v_mfma_f32_16x16x32_bf16 v[24:27], v[200:203], v[168:171], v[24:27]
	v_mfma_f32_16x16x32_bf16 v[16:19], v[192:195], v[176:179], v[16:19]
	v_mfma_f32_16x16x32_bf16 v[8:11], v[200:203], v[176:179], v[8:11]
	v_mfma_f32_16x16x32_bf16 v[4:7], v[192:195], v[184:187], v[4:7]
	v_mfma_f32_16x16x32_bf16 v[0:3], v[200:203], v[184:187], v[0:3]
	v_mfma_f32_16x16x32_bf16 v[48:51], v[196:199], v[164:167], v[48:51]
	v_mfma_f32_16x16x32_bf16 v[40:43], v[204:207], v[164:167], v[40:43]
	v_mfma_f32_16x16x32_bf16 v[32:35], v[196:199], v[172:175], v[32:35]
	v_mfma_f32_16x16x32_bf16 v[24:27], v[204:207], v[172:175], v[24:27]
	v_mfma_f32_16x16x32_bf16 v[16:19], v[196:199], v[180:183], v[16:19]
	v_mfma_f32_16x16x32_bf16 v[8:11], v[204:207], v[180:183], v[8:11]
	v_mfma_f32_16x16x32_bf16 v[4:7], v[196:199], v[188:191], v[4:7]
	v_mfma_f32_16x16x32_bf16 v[0:3], v[204:207], v[188:191], v[0:3]
	s_add_i32 s6, s6, 2
	s_addk_i32 s56, 0x100
	s_addk_i32 s7, 0x100
	s_cmp_gt_u32 s6, 5
	s_barrier
	s_cbranch_scc0 .LBB0_104
; DI unsigned pk2(float lo, float hi) { unsigned r; asm("v_cvt_pk_bf16_f32 %0, %1, %2" : "=v"(r) : "v"(lo), "v"(hi)); return r; }
;   DI void epi(const Acc& acc, const Unit& u, int wr, int wc, int fr, int fq) const {
; #pragma unroll
;     for (int ai = 0; ai < 2; ++ai)
; #pragma unroll
;       for (int m = 0; m < 4; ++m) {
;         const int row = u.pm * 256 + ai * HALF + wr * 64 + m * 16 + fr;
; #pragma unroll
;         for (int bj = 0; bj < 2; ++bj) {
;           const int col = u.pn * 256 + bj * HALF + wc * 32 + 8 * fq;
;           const f32x4 v0 = acc[ai][bj][m][0], v1 = acc[ai][bj][m][1];
;           u32x4 o; o.x = pk2(v0.x, v0.y); o.y = pk2(v0.z, v0.w); o.z = pk2(v1.x, v1.y); o.w = pk2(v1.z, v1.w);
;           *(u32x4*)(Z + (size_t)row * NGATE + col) = o;
;         }
;       }
	v_mov_b32_e32 v135, v137
	v_mov_b32_e32 v134, v136
	s_lshl_b32 s0, s22, 8
	s_add_i32 s0, s0, s44
	v_add_u32_e32 v134, s0, v134
	s_lshl_b32 s0, s46, 8
	s_or_b32 s0, s0, s45
	v_cvt_pk_bf16_f32 v68, v68, v69
	v_cvt_pk_bf16_f32 v69, v70, v71
	v_cvt_pk_bf16_f32 v70, v64, v65
	v_add_u32_e32 v64, 0x80, v134
	v_lshl_add_u32 v140, v135, 3, s0
	v_ashrrev_i32_e32 v135, 31, v134
	v_ashrrev_i32_e32 v65, 31, v64
	v_lshlrev_b64 v[142:143], 14, v[134:135]
	v_ashrrev_i32_e32 v141, 31, v140
	v_lshlrev_b64 v[64:65], 14, v[64:65]
	v_cvt_pk_bf16_f32 v124, v124, v125
	v_cvt_pk_bf16_f32 v125, v126, v127
	v_cvt_pk_bf16_f32 v126, v120, v121
	v_cvt_pk_bf16_f32 v127, v122, v123
	v_lshl_add_u64 v[122:123], s[26:27], 0, v[142:143]
	v_lshlrev_b64 v[120:121], 1, v[140:141]
	v_cvt_pk_bf16_f32 v112, v112, v113
	v_cvt_pk_bf16_f32 v113, v114, v115
	v_cvt_pk_bf16_f32 v114, v104, v105
	v_add_u32_e32 v104, 16, v134
	v_cvt_pk_bf16_f32 v60, v60, v61
	v_cvt_pk_bf16_f32 v61, v62, v63
	v_cvt_pk_bf16_f32 v62, v56, v57
	v_lshl_add_u64 v[56:57], s[26:27], 0, v[64:65]
	v_cvt_pk_bf16_f32 v48, v48, v49
	v_cvt_pk_bf16_f32 v49, v50, v51
	v_cvt_pk_bf16_f32 v50, v40, v41
	v_add_u32_e32 v40, 0x90, v134
	v_lshl_add_u64 v[122:123], v[122:123], 0, v[120:121]
	v_ashrrev_i32_e32 v105, 31, v104
	v_lshl_add_u64 v[56:57], v[56:57], 0, v[120:121]
	v_ashrrev_i32_e32 v41, 31, v40
	v_cvt_pk_bf16_f32 v115, v106, v107
	global_store_dwordx4 v[122:123], v[112:115], off offset:256
	v_cvt_pk_bf16_f32 v51, v42, v43
	global_store_dwordx4 v[56:57], v[48:51], off offset:256
	v_cvt_pk_bf16_f32 v106, v108, v109
	v_cvt_pk_bf16_f32 v96, v96, v97
	v_cvt_pk_bf16_f32 v97, v98, v99
	s_nop 0
	v_lshlrev_b64 v[112:113], 14, v[104:105]
	v_lshl_add_u64 v[108:109], s[26:27], 0, v[112:113]
	v_lshlrev_b64 v[48:49], 14, v[40:41]
	v_cvt_pk_bf16_f32 v98, v88, v89
	v_add_u32_e32 v88, 32, v134
	v_cvt_pk_bf16_f32 v42, v44, v45
	v_lshl_add_u64 v[44:45], s[26:27], 0, v[48:49]
	v_cvt_pk_bf16_f32 v32, v32, v33
	v_cvt_pk_bf16_f32 v33, v34, v35
	v_cvt_pk_bf16_f32 v34, v24, v25
	v_add_u32_e32 v24, 0xa0, v134
	v_lshl_add_u64 v[108:109], v[108:109], 0, v[120:121]
	v_ashrrev_i32_e32 v89, 31, v88
	v_lshl_add_u64 v[44:45], v[44:45], 0, v[120:121]
	v_ashrrev_i32_e32 v25, 31, v24
	v_cvt_pk_bf16_f32 v99, v90, v91
	global_store_dwordx4 v[108:109], v[96:99], off offset:256
	v_cvt_pk_bf16_f32 v35, v26, v27
	global_store_dwordx4 v[44:45], v[32:35], off offset:256
	v_cvt_pk_bf16_f32 v90, v92, v93
	v_cvt_pk_bf16_f32 v80, v80, v81
	v_cvt_pk_bf16_f32 v81, v82, v83
	s_nop 0
	v_lshlrev_b64 v[96:97], 14, v[88:89]
	v_lshl_add_u64 v[92:93], s[26:27], 0, v[96:97]
	v_lshlrev_b64 v[32:33], 14, v[24:25]
	v_cvt_pk_bf16_f32 v82, v72, v73
	v_add_u32_e32 v72, 48, v134
	v_cvt_pk_bf16_f32 v26, v28, v29
	v_lshl_add_u64 v[28:29], s[26:27], 0, v[32:33]
	v_cvt_pk_bf16_f32 v16, v16, v17
	v_cvt_pk_bf16_f32 v17, v18, v19
	v_cvt_pk_bf16_f32 v18, v8, v9
	v_add_u32_e32 v8, 0xb0, v134
	v_lshl_add_u64 v[92:93], v[92:93], 0, v[120:121]
	v_ashrrev_i32_e32 v73, 31, v72
	v_lshl_add_u64 v[28:29], v[28:29], 0, v[120:121]
	v_ashrrev_i32_e32 v9, 31, v8
	v_cvt_pk_bf16_f32 v83, v74, v75
	global_store_dwordx4 v[92:93], v[80:83], off offset:256
	v_cvt_pk_bf16_f32 v19, v10, v11
	global_store_dwordx4 v[28:29], v[16:19], off offset:256
	v_cvt_pk_bf16_f32 v74, v76, v77
	v_cvt_pk_bf16_f32 v10, v12, v13
	s_and_b64 vcc, exec, s[12:13]
	v_lshlrev_b64 v[80:81], 14, v[72:73]
	v_lshlrev_b64 v[16:17], 14, v[8:9]
	v_lshl_add_u64 v[76:77], s[26:27], 0, v[80:81]
	v_lshl_add_u64 v[12:13], s[26:27], 0, v[16:17]
	v_lshl_add_u64 v[76:77], v[76:77], 0, v[120:121]
	v_lshl_add_u64 v[12:13], v[12:13], 0, v[120:121]
	s_mov_b32 s46, s8
	s_mov_b32 s22, s16
	s_mov_b64 s[62:63], s[20:21]
	s_mov_b64 s[64:65], s[18:19]
	global_store_dwordx4 v[122:123], v[124:127], off
	v_cvt_pk_bf16_f32 v104, v116, v117
	v_cvt_pk_bf16_f32 v105, v118, v119
	v_cvt_pk_bf16_f32 v107, v110, v111
	global_store_dwordx4 v[108:109], v[104:107], off
	v_cvt_pk_bf16_f32 v88, v100, v101
	v_cvt_pk_bf16_f32 v89, v102, v103
	v_cvt_pk_bf16_f32 v91, v94, v95
	global_store_dwordx4 v[92:93], v[88:91], off
	v_cvt_pk_bf16_f32 v72, v84, v85
	v_cvt_pk_bf16_f32 v73, v86, v87
	v_cvt_pk_bf16_f32 v75, v78, v79
	global_store_dwordx4 v[76:77], v[72:75], off
	v_cvt_pk_bf16_f32 v71, v66, v67
	global_store_dwordx4 v[76:77], v[68:71], off offset:256
	v_cvt_pk_bf16_f32 v63, v58, v59
	global_store_dwordx4 v[56:57], v[60:63], off
	v_cvt_pk_bf16_f32 v40, v52, v53
	v_cvt_pk_bf16_f32 v41, v54, v55
	v_cvt_pk_bf16_f32 v43, v46, v47
	global_store_dwordx4 v[44:45], v[40:43], off
	v_cvt_pk_bf16_f32 v24, v36, v37
	v_cvt_pk_bf16_f32 v25, v38, v39
	v_cvt_pk_bf16_f32 v27, v30, v31
	global_store_dwordx4 v[28:29], v[24:27], off
	v_cvt_pk_bf16_f32 v8, v20, v21
	v_cvt_pk_bf16_f32 v9, v22, v23
	v_cvt_pk_bf16_f32 v11, v14, v15
	global_store_dwordx4 v[12:13], v[8:11], off
	v_cvt_pk_bf16_f32 v4, v4, v5
	v_cvt_pk_bf16_f32 v5, v6, v7
	v_cvt_pk_bf16_f32 v6, v0, v1
	v_cvt_pk_bf16_f32 v7, v2, v3
	global_store_dwordx4 v[12:13], v[4:7], off offset:256
	s_cbranch_vccz .LBB0_101
	s_setprio 0
	s_waitcnt vmcnt(0)
	v_readlane_b32 s44, v255, 6
	s_cmpk_gt_u32 s4, 0xff
	v_readlane_b32 s45, v255, 7
	s_cbranch_scc1 .LBB0_108
	s_barrier

; #define G_STAGE(bufoff, gbase, voff) do { _Pragma("unroll") for (int _i = 0; _i < 2; ++_i) \
;         __builtin_amdgcn_global_load_lds((const unsigned*)((const char*)(gbase) + (voff)[_i]), (LAS unsigned*)(lds + (bufoff) + ldsw + _i * 8192), 16, 0, 0); } while (0)
; #define G_LDA(dst, b, h) do { _Pragma("unroll") for (int m = 0; m < 4; ++m) _Pragma("unroll") for (int k = 0; k < 2; ++k) dst[m][k] = *(const LAS bf16x8*)(lds + G_SA(b, h) + aoff + m * 2048 + k * 1024); } while (0)
; #define G_LDB(dst, b, h) do { _Pragma("unroll") for (int n = 0; n < 2; ++n) _Pragma("unroll") for (int k = 0; k < 2; ++k) dst[n][k] = *(const LAS bf16x8*)(lds + G_SB(b, h) + boff + n * 2048 + k * 1024); } while (0)
; #define G_MMA(ai, bj, At, Bt) do { __builtin_amdgcn_s_setprio(1); _Pragma("unroll") for (int m = 0; m < 4; ++m) _Pragma("unroll") for (int n = 0; n < 2; ++n) _Pragma("unroll") for (int k = 0; k < 2; ++k) \
;         acc[ai][bj][m][n] = __builtin_amdgcn_mfma_f32_16x16x32_bf16(Bt[n][k], At[m][k], acc[ai][bj][m][n], 0, 0, 0); __builtin_amdgcn_s_setprio(0); } while (0)
; #define G_WAIT_L(n) asm volatile("s_waitcnt lgkmcnt(" #n ")" ::: "memory")
; #define G_BAR __builtin_amdgcn_s_barrier()
; #define G_SCHED __builtin_amdgcn_sched_barrier(0)
; template <class J>
; DI void gemm_phase(LAS unsigned char* lds, const J& job) {
;     ...
;       const bool last = (t == nt - 2);
;       const char* a1 = cA + G_KT(t + 1);
;       const char* a2 = last ? nA + G_KT(0) : cA + G_KT(t + 2); const char* b2 = last ? nB + G_KT(0) : cB + G_KT(t + 2);
;       const char* a3 = last ? nA + G_KT(1) : cA + G_KT(t + 3); const char* b3 = last ? nB + G_KT(1) : cB + G_KT(t + 3);
;       G_LDB(B0, 0, 0); G_SCHED; G_LDA(At, 0, 0); G_STAGE(G_SA(1, 1), a1 + hstepA, voffA);
;       G_WAIT_L(8); G_BAR; G_WAIT_L(0); G_MMA(0, 0, At, B0); G_BAR; G_SCHED;
;       G_LDB(B1, 0, 1); G_STAGE(G_SB(0, 0), b2, voffB);
;       G_BAR; G_WAIT_L(0); G_MMA(0, 1, At, B1); G_BAR;
;       G_LDA(At, 0, 1); G_STAGE(G_SA(0, 0), a2, voffA);
;       G_BAR; G_WAIT_L(0); G_MMA(1, 0, At, B0); G_BAR; G_SCHED;
.LBB0_282:
	s_add_i32 s1, s56, 0xffffff80
	s_and_b32 s0, s7, 0xf80
	s_and_b32 s1, s1, 0xf00
	s_add_u32 s10, s68, s1
	s_addc_u32 s11, s69, 0
	s_add_u32 s1, s66, s1
	s_addc_u32 s57, s67, 0
	s_and_b32 s70, s56, 0xf80
	s_add_u32 s71, s68, s70
	s_addc_u32 s72, s69, 0
	s_add_u32 s70, s66, s70
	s_addc_u32 s80, s67, 0
	s_cmp_eq_u32 s6, 28
	s_cselect_b32 s75, s46, s11
	s_cselect_b32 s74, s21, s10
	s_cselect_b32 s77, s96, s57
	s_cselect_b32 s76, s47, s1
	s_cselect_b32 s73, s97, s72
	s_cselect_b32 s72, s33, s71
	s_cselect_b32 s71, vcc_hi, s80
	s_cselect_b32 s70, vcc_lo, s70
	s_add_i32 s1, s84, 0x100
	v_add_u32_e32 v142, s1, v150
	ds_read_b128 v[134:137], v142
	ds_read_b128 v[138:141], v142 offset:1024
	ds_read_b128 v[152:155], v142 offset:2048
	ds_read_b128 v[156:159], v142 offset:3072
	s_add_u32 s10, s9, s0
	s_addc_u32 s11, s19, 0
	s_add_i32 m0, s15, 0xc000
	ds_read_b128 v[160:163], v151
	ds_read_b128 v[164:167], v151 offset:1024
	ds_read_b128 v[168:171], v151 offset:2048
	ds_read_b128 v[172:175], v151 offset:3072
	ds_read_b128 v[176:179], v151 offset:4096
	ds_read_b128 v[180:183], v151 offset:5120
	ds_read_b128 v[184:187], v151 offset:6144
	ds_read_b128 v[188:191], v151 offset:7168
	global_load_lds_dwordx4 v128, s[10:11]
	s_add_i32 m0, s15, 0xe000
	s_nop 0
	global_load_lds_dwordx4 v130, s[10:11]
	s_waitcnt lgkmcnt(8)
	s_barrier
	s_waitcnt lgkmcnt(0)
	v_mfma_f32_16x16x32_bf16 v[124:127], v[134:137], v[160:163], v[124:127]
	v_mfma_f32_16x16x32_bf16 v[120:123], v[152:155], v[160:163], v[120:123]
	v_mfma_f32_16x16x32_bf16 v[108:111], v[134:137], v[168:171], v[108:111]
	v_mfma_f32_16x16x32_bf16 v[104:107], v[152:155], v[168:171], v[104:107]
	v_mfma_f32_16x16x32_bf16 v[92:95], v[134:137], v[176:179], v[92:95]
	v_mfma_f32_16x16x32_bf16 v[88:91], v[152:155], v[176:179], v[88:91]
	v_mfma_f32_16x16x32_bf16 v[76:79], v[134:137], v[184:187], v[76:79]
	v_mfma_f32_16x16x32_bf16 v[72:75], v[152:155], v[184:187], v[72:75]
	v_mfma_f32_16x16x32_bf16 v[124:127], v[138:141], v[164:167], v[124:127]
	v_mfma_f32_16x16x32_bf16 v[120:123], v[156:159], v[164:167], v[120:123]
	v_mfma_f32_16x16x32_bf16 v[108:111], v[138:141], v[172:175], v[108:111]
	v_mfma_f32_16x16x32_bf16 v[104:107], v[156:159], v[172:175], v[104:107]
	v_mfma_f32_16x16x32_bf16 v[92:95], v[138:141], v[180:183], v[92:95]
	v_mfma_f32_16x16x32_bf16 v[88:91], v[156:159], v[180:183], v[88:91]
	v_mfma_f32_16x16x32_bf16 v[76:79], v[138:141], v[188:191], v[76:79]
	v_mfma_f32_16x16x32_bf16 v[72:75], v[156:159], v[188:191], v[72:75]
	s_barrier
	s_add_i32 s0, s85, 0x100
	v_add_u32_e32 v142, s0, v150
	s_add_i32 s1, s1, s5
	ds_read_b128 v[192:195], v142
	ds_read_b128 v[196:199], v142 offset:1024
	ds_read_b128 v[200:203], v142 offset:2048
	ds_read_b128 v[204:207], v142 offset:3072
	s_mov_b32 m0, s1
	s_nop 0
	global_load_lds_dwordx4 v146, s[76:77]
	s_add_i32 m0, s1, 0x2000
	s_nop 0
	global_load_lds_dwordx4 v132, s[76:77]
	s_barrier
	s_waitcnt lgkmcnt(0)
	v_mfma_f32_16x16x32_bf16 v[116:119], v[192:195], v[160:163], v[116:119]
	v_mfma_f32_16x16x32_bf16 v[112:115], v[200:203], v[160:163], v[112:115]
	v_mfma_f32_16x16x32_bf16 v[100:103], v[192:195], v[168:171], v[100:103]
	v_mfma_f32_16x16x32_bf16 v[96:99], v[200:203], v[168:171], v[96:99]
	v_mfma_f32_16x16x32_bf16 v[84:87], v[192:195], v[176:179], v[84:87]
	v_mfma_f32_16x16x32_bf16 v[80:83], v[200:203], v[176:179], v[80:83]
	v_mfma_f32_16x16x32_bf16 v[68:71], v[192:195], v[184:187], v[68:71]
	v_mfma_f32_16x16x32_bf16 v[64:67], v[200:203], v[184:187], v[64:67]
	v_mfma_f32_16x16x32_bf16 v[116:119], v[196:199], v[164:167], v[116:119]
	v_mfma_f32_16x16x32_bf16 v[112:115], v[204:207], v[164:167], v[112:115]
	v_mfma_f32_16x16x32_bf16 v[100:103], v[196:199], v[172:175], v[100:103]
	v_mfma_f32_16x16x32_bf16 v[96:99], v[204:207], v[172:175], v[96:99]
	v_mfma_f32_16x16x32_bf16 v[84:87], v[196:199], v[180:183], v[84:87]
	v_mfma_f32_16x16x32_bf16 v[80:83], v[204:207], v[180:183], v[80:83]
	v_mfma_f32_16x16x32_bf16 v[68:71], v[196:199], v[188:191], v[68:71]
	v_mfma_f32_16x16x32_bf16 v[64:67], v[204:207], v[188:191], v[64:67]
	s_mov_b32 m0, s15
	s_barrier
	ds_read_b128 v[160:163], v151 offset:16384
	ds_read_b128 v[164:167], v151 offset:17408
	ds_read_b128 v[168:171], v151 offset:18432
	ds_read_b128 v[172:175], v151 offset:19456
	ds_read_b128 v[176:179], v151 offset:20480
	ds_read_b128 v[180:183], v151 offset:21504
	ds_read_b128 v[184:187], v151 offset:22528
	ds_read_b128 v[188:191], v151 offset:23552
	global_load_lds_dwordx4 v128, s[74:75]
	s_mov_b32 m0, s24
	s_nop 0
	global_load_lds_dwordx4 v130, s[74:75]
	s_barrier
	s_waitcnt lgkmcnt(0)
	v_mfma_f32_16x16x32_bf16 v[60:63], v[134:137], v[160:163], v[60:63]
	v_mfma_f32_16x16x32_bf16 v[56:59], v[152:155], v[160:163], v[56:59]
	v_mfma_f32_16x16x32_bf16 v[44:47], v[134:137], v[168:171], v[44:47]
	v_mfma_f32_16x16x32_bf16 v[40:43], v[152:155], v[168:171], v[40:43]
	v_mfma_f32_16x16x32_bf16 v[28:31], v[134:137], v[176:179], v[28:31]
	v_mfma_f32_16x16x32_bf16 v[24:27], v[152:155], v[176:179], v[24:27]
	v_mfma_f32_16x16x32_bf16 v[12:15], v[134:137], v[184:187], v[12:15]
	v_mfma_f32_16x16x32_bf16 v[8:11], v[152:155], v[184:187], v[8:11]
	v_mfma_f32_16x16x32_bf16 v[60:63], v[138:141], v[164:167], v[60:63]
	v_mfma_f32_16x16x32_bf16 v[56:59], v[156:159], v[164:167], v[56:59]
	v_mfma_f32_16x16x32_bf16 v[44:47], v[138:141], v[172:175], v[44:47]
	v_mfma_f32_16x16x32_bf16 v[40:43], v[156:159], v[172:175], v[40:43]
	v_mfma_f32_16x16x32_bf16 v[28:31], v[138:141], v[180:183], v[28:31]
	v_mfma_f32_16x16x32_bf16 v[24:27], v[156:159], v[180:183], v[24:27]
	v_mfma_f32_16x16x32_bf16 v[12:15], v[138:141], v[188:191], v[12:15]
	v_mfma_f32_16x16x32_bf16 v[8:11], v[156:159], v[188:191], v[8:11]
	s_barrier
; #define G_STAGE(bufoff, gbase, voff) do { _Pragma("unroll") for (int _i = 0; _i < 2; ++_i) \
;         __builtin_amdgcn_global_load_lds((const unsigned*)((const char*)(gbase) + (voff)[_i]), (LAS unsigned*)(lds + (bufoff) + ldsw + _i * 8192), 16, 0, 0); } while (0)
; #define G_LDA(dst, b, h) do { _Pragma("unroll") for (int m = 0; m < 4; ++m) _Pragma("unroll") for (int k = 0; k < 2; ++k) dst[m][k] = *(const LAS bf16x8*)(lds + G_SA(b, h) + aoff + m * 2048 + k * 1024); } while (0)
; #define G_LDB(dst, b, h) do { _Pragma("unroll") for (int n = 0; n < 2; ++n) _Pragma("unroll") for (int k = 0; k < 2; ++k) dst[n][k] = *(const LAS bf16x8*)(lds + G_SB(b, h) + boff + n * 2048 + k * 1024); } while (0)
; #define G_MMA(ai, bj, At, Bt) do { __builtin_amdgcn_s_setprio(1); _Pragma("unroll") for (int m = 0; m < 4; ++m) _Pragma("unroll") for (int n = 0; n < 2; ++n) _Pragma("unroll") for (int k = 0; k < 2; ++k) \
;         acc[ai][bj][m][n] = __builtin_amdgcn_mfma_f32_16x16x32_bf16(Bt[n][k], At[m][k], acc[ai][bj][m][n], 0, 0, 0); __builtin_amdgcn_s_setprio(0); } while (0)
; #define G_WAIT_V(n) asm volatile("s_waitcnt vmcnt(" #n ")" ::: "memory")
; #define G_WAIT_L(n) asm volatile("s_waitcnt lgkmcnt(" #n ")" ::: "memory")
; #define G_BAR __builtin_amdgcn_s_barrier()
; #define G_SCHED __builtin_amdgcn_sched_barrier(0)
; template <class J>
; DI void gemm_phase(LAS unsigned char* lds, const J& job) {
;     ...
;       G_STAGE(G_SB(0, 1), b2 + hstepB, voffB);
;       G_WAIT_V(6); G_BAR; G_MMA(1, 1, At, B1); G_BAR;
;       G_LDB(B0, 1, 0); G_SCHED; G_LDA(At, 1, 0); G_STAGE(G_SA(0, 1), a2 + hstepA, voffA);
;       G_WAIT_L(8); G_BAR; G_WAIT_L(0); G_MMA(0, 0, At, B0); G_BAR; G_SCHED;
;       G_LDB(B1, 1, 1); G_STAGE(G_SB(1, 0), b3, voffB);
;       G_BAR; G_WAIT_L(0); G_MMA(0, 1, At, B1); G_BAR;
;       G_LDA(At, 1, 1); G_STAGE(G_SA(1, 0), a3, voffA);
	s_add_u32 s10, s76, 0x80000
	s_addc_u32 s11, s77, 0
	s_add_i32 s0, s0, s5
	s_mov_b32 m0, s0
	s_nop 0
	global_load_lds_dwordx4 v146, s[10:11]
	s_add_i32 m0, s0, 0x2000
	s_nop 0
	global_load_lds_dwordx4 v132, s[10:11]
	s_waitcnt vmcnt(6)
	s_barrier
	v_mfma_f32_16x16x32_bf16 v[52:55], v[192:195], v[160:163], v[52:55]
	v_mfma_f32_16x16x32_bf16 v[48:51], v[200:203], v[160:163], v[48:51]
	v_mfma_f32_16x16x32_bf16 v[36:39], v[192:195], v[168:171], v[36:39]
	v_mfma_f32_16x16x32_bf16 v[32:35], v[200:203], v[168:171], v[32:35]
	v_mfma_f32_16x16x32_bf16 v[20:23], v[192:195], v[176:179], v[20:23]
	v_mfma_f32_16x16x32_bf16 v[16:19], v[200:203], v[176:179], v[16:19]
	v_mfma_f32_16x16x32_bf16 v[4:7], v[192:195], v[184:187], v[4:7]
	v_mfma_f32_16x16x32_bf16 v[0:3], v[200:203], v[184:187], v[0:3]
	v_mfma_f32_16x16x32_bf16 v[52:55], v[196:199], v[164:167], v[52:55]
	v_mfma_f32_16x16x32_bf16 v[48:51], v[204:207], v[164:167], v[48:51]
	v_mfma_f32_16x16x32_bf16 v[36:39], v[196:199], v[172:175], v[36:39]
	v_mfma_f32_16x16x32_bf16 v[32:35], v[204:207], v[172:175], v[32:35]
	v_mfma_f32_16x16x32_bf16 v[20:23], v[196:199], v[180:183], v[20:23]
	v_mfma_f32_16x16x32_bf16 v[16:19], v[204:207], v[180:183], v[16:19]
	v_mfma_f32_16x16x32_bf16 v[4:7], v[196:199], v[188:191], v[4:7]
	v_mfma_f32_16x16x32_bf16 v[0:3], v[204:207], v[188:191], v[0:3]
	s_add_i32 s0, s88, 0x100
	v_add_u32_e32 v142, s0, v150
	s_barrier
	ds_read_b128 v[134:137], v142
	ds_read_b128 v[138:141], v142 offset:1024
	ds_read_b128 v[152:155], v142 offset:2048
	ds_read_b128 v[156:159], v142 offset:3072
	s_add_u32 s10, s74, 0x80000
	s_addc_u32 s11, s75, 0
	s_mov_b32 m0, s25
	ds_read_b128 v[160:163], v151 offset:32768
	ds_read_b128 v[164:167], v151 offset:33792
	ds_read_b128 v[168:171], v151 offset:34816
	ds_read_b128 v[172:175], v151 offset:35840
	ds_read_b128 v[176:179], v151 offset:36864
	ds_read_b128 v[180:183], v151 offset:37888
	ds_read_b128 v[184:187], v151 offset:38912
	ds_read_b128 v[188:191], v151 offset:39936
	global_load_lds_dwordx4 v128, s[10:11]
	s_mov_b32 m0, s36
	s_nop 0
	global_load_lds_dwordx4 v130, s[10:11]
	s_waitcnt lgkmcnt(8)
	s_barrier
	s_waitcnt lgkmcnt(0)
	v_mfma_f32_16x16x32_bf16 v[124:127], v[134:137], v[160:163], v[124:127]
	v_mfma_f32_16x16x32_bf16 v[120:123], v[152:155], v[160:163], v[120:123]
	v_mfma_f32_16x16x32_bf16 v[108:111], v[134:137], v[168:171], v[108:111]
	v_mfma_f32_16x16x32_bf16 v[104:107], v[152:155], v[168:171], v[104:107]
	v_mfma_f32_16x16x32_bf16 v[92:95], v[134:137], v[176:179], v[92:95]
	v_mfma_f32_16x16x32_bf16 v[88:91], v[152:155], v[176:179], v[88:91]
	v_mfma_f32_16x16x32_bf16 v[76:79], v[134:137], v[184:187], v[76:79]
	v_mfma_f32_16x16x32_bf16 v[72:75], v[152:155], v[184:187], v[72:75]
	v_mfma_f32_16x16x32_bf16 v[124:127], v[138:141], v[164:167], v[124:127]
	v_mfma_f32_16x16x32_bf16 v[120:123], v[156:159], v[164:167], v[120:123]
	v_mfma_f32_16x16x32_bf16 v[108:111], v[138:141], v[172:175], v[108:111]
	v_mfma_f32_16x16x32_bf16 v[104:107], v[156:159], v[172:175], v[104:107]
	v_mfma_f32_16x16x32_bf16 v[92:95], v[138:141], v[180:183], v[92:95]
	v_mfma_f32_16x16x32_bf16 v[88:91], v[156:159], v[180:183], v[88:91]
	v_mfma_f32_16x16x32_bf16 v[76:79], v[138:141], v[188:191], v[76:79]
	v_mfma_f32_16x16x32_bf16 v[72:75], v[156:159], v[188:191], v[72:75]
	s_barrier
	s_add_i32 s1, s89, 0x100
	v_add_u32_e32 v142, s1, v150
	s_add_i32 s0, s0, s5
	ds_read_b128 v[192:195], v142
	ds_read_b128 v[196:199], v142 offset:1024
	ds_read_b128 v[200:203], v142 offset:2048
	ds_read_b128 v[204:207], v142 offset:3072
	s_mov_b32 m0, s0
	s_nop 0
	global_load_lds_dwordx4 v146, s[70:71]
	s_add_i32 m0, s0, 0x2000
	s_nop 0
	global_load_lds_dwordx4 v132, s[70:71]
	s_barrier
	s_waitcnt lgkmcnt(0)
	v_mfma_f32_16x16x32_bf16 v[116:119], v[192:195], v[160:163], v[116:119]
	v_mfma_f32_16x16x32_bf16 v[112:115], v[200:203], v[160:163], v[112:115]
	v_mfma_f32_16x16x32_bf16 v[100:103], v[192:195], v[168:171], v[100:103]
	v_mfma_f32_16x16x32_bf16 v[96:99], v[200:203], v[168:171], v[96:99]
	v_mfma_f32_16x16x32_bf16 v[84:87], v[192:195], v[176:179], v[84:87]
	v_mfma_f32_16x16x32_bf16 v[80:83], v[200:203], v[176:179], v[80:83]
	v_mfma_f32_16x16x32_bf16 v[68:71], v[192:195], v[184:187], v[68:71]
	v_mfma_f32_16x16x32_bf16 v[64:67], v[200:203], v[184:187], v[64:67]
	v_mfma_f32_16x16x32_bf16 v[116:119], v[196:199], v[164:167], v[116:119]
	v_mfma_f32_16x16x32_bf16 v[112:115], v[204:207], v[164:167], v[112:115]
	v_mfma_f32_16x16x32_bf16 v[100:103], v[196:199], v[172:175], v[100:103]
	v_mfma_f32_16x16x32_bf16 v[96:99], v[204:207], v[172:175], v[96:99]
	v_mfma_f32_16x16x32_bf16 v[84:87], v[196:199], v[180:183], v[84:87]
	v_mfma_f32_16x16x32_bf16 v[80:83], v[204:207], v[180:183], v[80:83]
	v_mfma_f32_16x16x32_bf16 v[68:71], v[196:199], v[188:191], v[68:71]
	v_mfma_f32_16x16x32_bf16 v[64:67], v[204:207], v[188:191], v[64:67]
	s_mov_b32 m0, s45
	s_barrier
; DI unsigned pk2(float lo, float hi) { unsigned r; asm("v_cvt_pk_bf16_f32 %0, %1, %2" : "=v"(r) : "v"(lo), "v"(hi)); return r; }
; #define G_STAGE(bufoff, gbase, voff) do { _Pragma("unroll") for (int _i = 0; _i < 2; ++_i) \
;         __builtin_amdgcn_global_load_lds((const unsigned*)((const char*)(gbase) + (voff)[_i]), (LAS unsigned*)(lds + (bufoff) + ldsw + _i * 8192), 16, 0, 0); } while (0)
; #define G_MMA(ai, bj, At, Bt) do { __builtin_amdgcn_s_setprio(1); _Pragma("unroll") for (int m = 0; m < 4; ++m) _Pragma("unroll") for (int n = 0; n < 2; ++n) _Pragma("unroll") for (int k = 0; k < 2; ++k) \
;         acc[ai][bj][m][n] = __builtin_amdgcn_mfma_f32_16x16x32_bf16(Bt[n][k], At[m][k], acc[ai][bj][m][n], 0, 0, 0); __builtin_amdgcn_s_setprio(0); } while (0)
; #define G_WAIT_V(n) asm volatile("s_waitcnt vmcnt(" #n ")" ::: "memory")
; #define G_WAIT_L(n) asm volatile("s_waitcnt lgkmcnt(" #n ")" ::: "memory")
; #define G_BAR __builtin_amdgcn_s_barrier()
; #define G_SCHED __builtin_amdgcn_sched_barrier(0)
; template <class J>
; DI void gemm_phase(LAS unsigned char* lds, const J& job) {
;     ...
;       G_BAR; G_WAIT_L(0); G_MMA(1, 0, At, B0); G_BAR; G_SCHED;
;       G_STAGE(G_SB(1, 1), b3 + hstepB, voffB);
;       G_WAIT_V(6); G_BAR; G_MMA(1, 1, At, B1); G_BAR;
;   DI void epi(const Acc& acc, const Unit& u, int wr, int wc, int fr, int fq) const {
; #pragma unroll
;     for (int ai = 0; ai < 2; ++ai)
; #pragma unroll
;       for (int m = 0; m < 4; ++m) {
;         const int rl = ai * HALF + wr * 64 + m * 16 + fr;
; #pragma unroll
;         for (int bj = 0; bj < 2; ++bj) {
;           const int col = u.pn * 256 + bj * HALF + wc * 32 + 8 * fq;
;           const f32x4 v0 = acc[ai][bj][m][0], v1 = acc[ai][bj][m][1];
;           const int row = u.pm * 256 + rl;
;           u32x4 o; o.x = pk2(v0.x, v0.y); o.y = pk2(v0.z, v0.w); o.z = pk2(v1.x, v1.y); o.w = pk2(v1.z, v1.w);
;           *(u32x4*)(proj + (size_t)row * NPROJ + col) = o;
;           if (u.pn >= 8 && u.pn < 12) {
;             const int isv = u.pn >= 10; const int cc = col - (isv ? C_BV : C_BK);
;             float* dst = out + (isv ? O_VP : O_KP) + ((size_t)l * TP + row) * 512 + cc;
;             *(f32x4*)dst = v0; *(f32x4*)(dst + 4) = v1;
	ds_read_b128 v[160:163], v151 offset:49152
	ds_read_b128 v[164:167], v151 offset:50176
	ds_read_b128 v[168:171], v151 offset:51200
	ds_read_b128 v[172:175], v151 offset:52224
	ds_read_b128 v[176:179], v151 offset:53248
	ds_read_b128 v[180:183], v151 offset:54272
	ds_read_b128 v[184:187], v151 offset:55296
	ds_read_b128 v[188:191], v151 offset:56320
	global_load_lds_dwordx4 v128, s[72:73]
	s_mov_b32 m0, s65
	s_nop 0
	global_load_lds_dwordx4 v130, s[72:73]
	s_barrier
	s_waitcnt lgkmcnt(0)
	v_mfma_f32_16x16x32_bf16 v[60:63], v[134:137], v[160:163], v[60:63]
	v_mfma_f32_16x16x32_bf16 v[56:59], v[152:155], v[160:163], v[56:59]
	v_mfma_f32_16x16x32_bf16 v[44:47], v[134:137], v[168:171], v[44:47]
	v_mfma_f32_16x16x32_bf16 v[40:43], v[152:155], v[168:171], v[40:43]
	v_mfma_f32_16x16x32_bf16 v[28:31], v[134:137], v[176:179], v[28:31]
	v_mfma_f32_16x16x32_bf16 v[24:27], v[152:155], v[176:179], v[24:27]
	v_mfma_f32_16x16x32_bf16 v[12:15], v[134:137], v[184:187], v[12:15]
	v_mfma_f32_16x16x32_bf16 v[8:11], v[152:155], v[184:187], v[8:11]
	v_mfma_f32_16x16x32_bf16 v[60:63], v[138:141], v[164:167], v[60:63]
	v_mfma_f32_16x16x32_bf16 v[56:59], v[156:159], v[164:167], v[56:59]
	v_mfma_f32_16x16x32_bf16 v[44:47], v[138:141], v[172:175], v[44:47]
	v_mfma_f32_16x16x32_bf16 v[40:43], v[156:159], v[172:175], v[40:43]
	v_mfma_f32_16x16x32_bf16 v[28:31], v[138:141], v[180:183], v[28:31]
	v_mfma_f32_16x16x32_bf16 v[24:27], v[156:159], v[180:183], v[24:27]
	v_mfma_f32_16x16x32_bf16 v[12:15], v[138:141], v[188:191], v[12:15]
	v_mfma_f32_16x16x32_bf16 v[8:11], v[156:159], v[188:191], v[8:11]
	s_barrier
	s_add_u32 s10, s70, 0x80000
	s_addc_u32 s11, s71, 0
	s_add_i32 s0, s1, s5
	s_mov_b32 m0, s0
	s_nop 0
	global_load_lds_dwordx4 v146, s[10:11]
	s_add_i32 m0, s0, 0x2000
	s_nop 0
	global_load_lds_dwordx4 v132, s[10:11]
	s_waitcnt vmcnt(6)
	s_barrier
	v_mfma_f32_16x16x32_bf16 v[52:55], v[192:195], v[160:163], v[52:55]
	v_mfma_f32_16x16x32_bf16 v[48:51], v[200:203], v[160:163], v[48:51]
	v_mfma_f32_16x16x32_bf16 v[36:39], v[192:195], v[168:171], v[36:39]
	v_mfma_f32_16x16x32_bf16 v[32:35], v[200:203], v[168:171], v[32:35]
	v_mfma_f32_16x16x32_bf16 v[20:23], v[192:195], v[176:179], v[20:23]
	v_mfma_f32_16x16x32_bf16 v[16:19], v[200:203], v[176:179], v[16:19]
	v_mfma_f32_16x16x32_bf16 v[4:7], v[192:195], v[184:187], v[4:7]
	v_mfma_f32_16x16x32_bf16 v[0:3], v[200:203], v[184:187], v[0:3]
	v_mfma_f32_16x16x32_bf16 v[52:55], v[196:199], v[164:167], v[52:55]
	v_mfma_f32_16x16x32_bf16 v[48:51], v[204:207], v[164:167], v[48:51]
	v_mfma_f32_16x16x32_bf16 v[36:39], v[196:199], v[172:175], v[36:39]
	v_mfma_f32_16x16x32_bf16 v[32:35], v[204:207], v[172:175], v[32:35]
	v_mfma_f32_16x16x32_bf16 v[20:23], v[196:199], v[180:183], v[20:23]
	v_mfma_f32_16x16x32_bf16 v[16:19], v[204:207], v[180:183], v[16:19]
	v_mfma_f32_16x16x32_bf16 v[4:7], v[196:199], v[188:191], v[4:7]
	v_mfma_f32_16x16x32_bf16 v[0:3], v[204:207], v[188:191], v[0:3]
	s_add_i32 s6, s6, 2
	s_addk_i32 s56, 0x100
	s_addk_i32 s7, 0x100
	s_cmp_gt_u32 s6, 29
	s_barrier
	s_cbranch_scc0 .LBB0_282
	v_mov_b32_e32 v135, v148
	v_mov_b32_e32 v134, v149
	s_lshl_b32 s0, s64, 8
	s_or_b32 s0, s0, s38
	v_lshl_add_u32 v134, v134, 3, s0
	s_lshl_b32 s0, s8, 8
	s_add_i32 s0, s0, s37
	v_add_u32_e32 v136, s0, v135
	s_and_b32 s0, s64, -4
	s_cmp_eq_u32 s0, 8
	s_cselect_b64 s[66:67], -1, 0
	s_cmp_gt_u32 s64, 9
	s_cselect_b64 s[6:7], -1, 0
	s_and_b64 s[6:7], s[6:7], exec
	s_movk_i32 s1, 0xf600
	v_mov_b64_e32 v[138:139], s[26:27]
	s_cselect_b32 s7, s1, 0xfffff800
	s_mov_b32 s1, 0x3040000
	v_ashrrev_i32_e32 v137, 31, v136
	v_mad_i64_i32 v[138:139], s[8:9], v136, s92, v[138:139]
	v_ashrrev_i32_e32 v135, 31, v134
	s_cselect_b32 s6, s1, 0x2040000
	s_cmp_lg_u32 s0, 8
	v_lshlrev_b64 v[140:141], 11, v[136:137]
	v_lshl_add_u64 v[142:143], v[134:135], 1, v[138:139]
	v_add_u32_e32 v138, s7, v134
	v_cvt_pk_bf16_f32 v152, v124, v125
	v_cvt_pk_bf16_f32 v153, v126, v127
	v_cvt_pk_bf16_f32 v154, v120, v121
	v_cvt_pk_bf16_f32 v155, v122, v123
	global_store_dwordx4 v[142:143], v[152:155], off
	s_cbranch_scc1 .LBB0_285
	s_lshl_b32 s0, s6, 2
	s_add_u32 s8, s83, s0
	s_addc_u32 s9, s86, 0
	v_lshl_add_u64 v[152:153], s[8:9], 0, v[140:141]
	v_ashrrev_i32_e32 v139, 31, v138
	v_lshl_add_u64 v[152:153], v[138:139], 2, v[152:153]
	global_store_dwordx4 v[152:153], v[124:127], off
	global_store_dwordx4 v[152:153], v[120:123], off offset:16
